# in_proj epilogue rewritten: mode dispatch hoisted, straight-line 8-way interleaved; plus merge epilogue
# speedup vs baseline: 1.0107x; 1.0107x over previous
; __device__ __forceinline__ u32x4 pack8(const float* f) { u32x4 o; o.x = pk2(f[0], f[1]); o.y = pk2(f[2], f[3]); o.z = pk2(f[4], f[5]); o.w = pk2(f[6], f[7]); return o; }
; __device__ __forceinline__ float sigmoidf_(float x) { return rcpf(1.0f + __expf(-x)); }
; __device__ __forceinline__ float gelu_tanh(float v) { const float u = 0.7978845608f * (v + 0.044715f * v * v * v); return v * rcpf(1.0f + __expf(-2.0f * u)); }
;     __device__ __forceinline__ void operator()(const f32x4 (&acc)[2][2][4][2], const Unit& u, int wr, int wc, int fr, int fq) const {
;         const int row0 = u.pm * BM + wr * 64 + fr;
;         const int mode = u.pn < 4 ? 0 : (u.pn < 20 ? 1 : 2);
;         float rsv[2][4];
; #pragma unroll
;         for (int ai = 0; ai < 2; ++ai)
; #pragma unroll
;             for (int m = 0; m < 4; ++m) rsv[ai][m] = rst[u.ord * 256 + wr * 64 + fr + ai * HALF + m * 16];
; #pragma unroll
;         for (int ai = 0; ai < 2; ++ai)
; #pragma unroll
;             for (int m = 0; m < 4; ++m) { const size_t row = (size_t)(row0 + ai * HALF + m * 16); const float rs = rsv[ai][m];
; #pragma unroll
;                 for (int bj = 0; bj < 2; ++bj) { float o[8];
;                     const int c0 = u.pn * BM + bj * HALF + wc * 32 + 8 * fq;
; #pragma unroll
;                     for (int n = 0; n < 2; ++n)
; #pragma unroll
;                         for (int j = 0; j < 4; ++j) { const float v = acc[ai][bj][m][n][j] * rs; o[n * 4 + j] = mode == 0 ? gelu_tanh(v) : (mode == 1 ? v : sigmoidf_(v)); }
;                     if (mode == 2) { unsigned w0 = 0u, w1 = 0u;
; #pragma unroll
;                         for (int j = 0; j < 4; ++j) { w0 = __builtin_amdgcn_cvt_pk_u8_f32(fmaxf(o[j] * 255.f, 1.f), j, w0); w1 = __builtin_amdgcn_cvt_pk_u8_f32(fmaxf(o[4 + j] * 255.f, 1.f), j, w1); }
;                         u32x2 wv; wv.x = w0; wv.y = w1; *(u32x2*)(gates + row * 4096 + (c0 - 5120)) = wv; }
;                     else if (c0 < PLD) *(u32x4*)(proj + row * PLD + c0) = pack8(o); } }
.LBB0_438:
	s_cmp_lt_i32 s30, 20
	v_lshl_add_u32 v140, s39, 10, v150
	s_cselect_b32 s2, 1, 2
	ds_read2_b32 v[146:147], v140 offset1:16
	ds_read2_b32 v[144:145], v140 offset0:32 offset1:48
	ds_read2_b32 v[142:143], v140 offset0:128 offset1:144
	ds_read2_b32 v[140:141], v140 offset0:160 offset1:176
	s_cmp_gt_i32 s30, 3
	s_cselect_b32 s28, s2, 0
	s_mov_b64 s[64:65], s[88:89]
	v_lshl_add_u32 v153, s38, 8, v148
	s_cmp_eq_u32 s28, 2
	s_cbranch_scc1 .Lmy_ip_m2
	s_movk_i32 s2, 0x1320
	v_lshl_or_b32 v154, s30, 8, v151
	v_or_b32_e32 v155, 0x80, v154
	v_cmp_gt_i32_e64 s[24:25], s2, v154
	v_mul_lo_u32 v153, v153, s70
	v_cmp_gt_i32_e64 s[100:101], s2, v155
	v_lshl_add_u32 v153, v154, 1, v153
	s_cmp_eq_u32 s28, 1
	s_waitcnt lgkmcnt(0)
	s_cbranch_scc1 .Lmy_ip_m1
	s_mov_b32 s2, 0x3d372713
	s_mov_b32 s3, 0x3f4c422a
	s_mov_b32 s28, 0x3fb8aa3b
	v_mul_f32_e32 v126, v126, v146
	v_mul_f32_e32 v127, v127, v146
	v_mul_f32_e32 v128, v128, v146
	v_mul_f32_e32 v129, v129, v146
	v_mul_f32_e32 v122, v122, v146
	v_mul_f32_e32 v123, v123, v146
	v_mul_f32_e32 v124, v124, v146
	v_mul_f32_e32 v125, v125, v146
	v_mul_f32_e32 v156, s2, v126
	v_mul_f32_e32 v157, s2, v127
	v_mul_f32_e32 v158, s2, v128
	v_mul_f32_e32 v159, s2, v129
	v_mul_f32_e32 v160, s2, v122
	v_mul_f32_e32 v161, s2, v123
	v_mul_f32_e32 v162, s2, v124
	v_mul_f32_e32 v163, s2, v125
	v_mul_f32_e32 v156, v126, v156
	v_mul_f32_e32 v157, v127, v157
	v_mul_f32_e32 v158, v128, v158
	v_mul_f32_e32 v159, v129, v159
	v_mul_f32_e32 v160, v122, v160
	v_mul_f32_e32 v161, v123, v161
	v_mul_f32_e32 v162, v124, v162
	v_mul_f32_e32 v163, v125, v163
	v_fma_f32 v156, v126, v156, v126
	v_fma_f32 v157, v127, v157, v127
	v_fma_f32 v158, v128, v158, v128
	v_fma_f32 v159, v129, v159, v129
	v_fma_f32 v160, v122, v160, v122
	v_fma_f32 v161, v123, v161, v123
	v_fma_f32 v162, v124, v162, v124
	v_fma_f32 v163, v125, v163, v125
	v_mul_f32_e32 v156, s3, v156
	v_mul_f32_e32 v157, s3, v157
	v_mul_f32_e32 v158, s3, v158
	v_mul_f32_e32 v159, s3, v159
	v_mul_f32_e32 v160, s3, v160
	v_mul_f32_e32 v161, s3, v161
	v_mul_f32_e32 v162, s3, v162
	v_mul_f32_e32 v163, s3, v163
	v_mul_f32_e32 v156, -2.0, v156
	v_mul_f32_e32 v157, -2.0, v157
	v_mul_f32_e32 v158, -2.0, v158
	v_mul_f32_e32 v159, -2.0, v159
	v_mul_f32_e32 v160, -2.0, v160
	v_mul_f32_e32 v161, -2.0, v161
	v_mul_f32_e32 v162, -2.0, v162
	v_mul_f32_e32 v163, -2.0, v163
	v_mul_f32_e32 v156, s28, v156
	v_mul_f32_e32 v157, s28, v157
	v_mul_f32_e32 v158, s28, v158
	v_mul_f32_e32 v159, s28, v159
	v_mul_f32_e32 v160, s28, v160
	v_mul_f32_e32 v161, s28, v161
	v_mul_f32_e32 v162, s28, v162
	v_mul_f32_e32 v163, s28, v163
	v_exp_f32_e32 v156, v156
	v_exp_f32_e32 v157, v157
	v_exp_f32_e32 v158, v158
	v_exp_f32_e32 v159, v159
	v_exp_f32_e32 v160, v160
	v_exp_f32_e32 v161, v161
	v_exp_f32_e32 v162, v162
	v_exp_f32_e32 v163, v163
	v_add_f32_e32 v156, 1.0, v156
	v_add_f32_e32 v157, 1.0, v157
	v_add_f32_e32 v158, 1.0, v158
	v_add_f32_e32 v159, 1.0, v159
	v_add_f32_e32 v160, 1.0, v160
	v_add_f32_e32 v161, 1.0, v161
	v_add_f32_e32 v162, 1.0, v162
	v_add_f32_e32 v163, 1.0, v163
	v_rcp_f32_e32 v156, v156
	v_rcp_f32_e32 v157, v157
	v_rcp_f32_e32 v158, v158
	v_rcp_f32_e32 v159, v159
	v_rcp_f32_e32 v160, v160
	v_rcp_f32_e32 v161, v161
	v_rcp_f32_e32 v162, v162
	v_rcp_f32_e32 v163, v163
	v_mul_f32_e32 v126, v126, v156
	v_mul_f32_e32 v127, v127, v157
	v_mul_f32_e32 v128, v128, v158
	v_mul_f32_e32 v129, v129, v159
	v_mul_f32_e32 v122, v122, v160
	v_mul_f32_e32 v123, v123, v161
	v_mul_f32_e32 v124, v124, v162
	v_mul_f32_e32 v125, v125, v163
	v_cvt_pk_bf16_f32 v164, v126, v127
	v_cvt_pk_bf16_f32 v165, v128, v129
	v_cvt_pk_bf16_f32 v166, v122, v123
	v_cvt_pk_bf16_f32 v167, v124, v125
	s_mov_b64 exec, s[24:25]
	global_store_dwordx4 v153, v[164:167], s[68:69]
	s_mov_b64 exec, -1
	v_mul_f32_e32 v118, v118, v146
	v_mul_f32_e32 v119, v119, v146
	v_mul_f32_e32 v120, v120, v146
	v_mul_f32_e32 v121, v121, v146
	v_mul_f32_e32 v114, v114, v146
	v_mul_f32_e32 v115, v115, v146
	v_mul_f32_e32 v116, v116, v146
	v_mul_f32_e32 v117, v117, v146
	v_mul_f32_e32 v156, s2, v118
	v_mul_f32_e32 v157, s2, v119
	v_mul_f32_e32 v158, s2, v120
	v_mul_f32_e32 v159, s2, v121
	v_mul_f32_e32 v160, s2, v114
	v_mul_f32_e32 v161, s2, v115
	v_mul_f32_e32 v162, s2, v116
	v_mul_f32_e32 v163, s2, v117
	v_mul_f32_e32 v156, v118, v156
	v_mul_f32_e32 v157, v119, v157
	v_mul_f32_e32 v158, v120, v158
	v_mul_f32_e32 v159, v121, v159
	v_mul_f32_e32 v160, v114, v160
	v_mul_f32_e32 v161, v115, v161
	v_mul_f32_e32 v162, v116, v162
	v_mul_f32_e32 v163, v117, v163
	v_fma_f32 v156, v118, v156, v118
	v_fma_f32 v157, v119, v157, v119
	v_fma_f32 v158, v120, v158, v120
	v_fma_f32 v159, v121, v159, v121
	v_fma_f32 v160, v114, v160, v114
	v_fma_f32 v161, v115, v161, v115
	v_fma_f32 v162, v116, v162, v116
	v_fma_f32 v163, v117, v163, v117
	v_mul_f32_e32 v156, s3, v156
	v_mul_f32_e32 v157, s3, v157
	v_mul_f32_e32 v158, s3, v158
	v_mul_f32_e32 v159, s3, v159
	v_mul_f32_e32 v160, s3, v160
	v_mul_f32_e32 v161, s3, v161
	v_mul_f32_e32 v162, s3, v162
	v_mul_f32_e32 v163, s3, v163
	v_mul_f32_e32 v156, -2.0, v156
	v_mul_f32_e32 v157, -2.0, v157
	v_mul_f32_e32 v158, -2.0, v158
	v_mul_f32_e32 v159, -2.0, v159
	v_mul_f32_e32 v160, -2.0, v160
	v_mul_f32_e32 v161, -2.0, v161
	v_mul_f32_e32 v162, -2.0, v162
	v_mul_f32_e32 v163, -2.0, v163
	v_mul_f32_e32 v156, s28, v156
	v_mul_f32_e32 v157, s28, v157
	v_mul_f32_e32 v158, s28, v158
	v_mul_f32_e32 v159, s28, v159
	v_mul_f32_e32 v160, s28, v160
	v_mul_f32_e32 v161, s28, v161
	v_mul_f32_e32 v162, s28, v162
	v_mul_f32_e32 v163, s28, v163
	v_exp_f32_e32 v156, v156
	v_exp_f32_e32 v157, v157
	v_exp_f32_e32 v158, v158
	v_exp_f32_e32 v159, v159
; __device__ __forceinline__ u32x4 pack8(const float* f) { u32x4 o; o.x = pk2(f[0], f[1]); o.y = pk2(f[2], f[3]); o.z = pk2(f[4], f[5]); o.w = pk2(f[6], f[7]); return o; }
; __device__ __forceinline__ float sigmoidf_(float x) { return rcpf(1.0f + __expf(-x)); }
; __device__ __forceinline__ float gelu_tanh(float v) { const float u = 0.7978845608f * (v + 0.044715f * v * v * v); return v * rcpf(1.0f + __expf(-2.0f * u)); }
;     __device__ __forceinline__ void operator()(const f32x4 (&acc)[2][2][4][2], const Unit& u, int wr, int wc, int fr, int fq) const {
;     ...
;             for (int m = 0; m < 4; ++m) { const size_t row = (size_t)(row0 + ai * HALF + m * 16); const float rs = rsv[ai][m];
; #pragma unroll
;                 for (int bj = 0; bj < 2; ++bj) { float o[8];
;                     const int c0 = u.pn * BM + bj * HALF + wc * 32 + 8 * fq;
; #pragma unroll
;                     for (int n = 0; n < 2; ++n)
; #pragma unroll
;                         for (int j = 0; j < 4; ++j) { const float v = acc[ai][bj][m][n][j] * rs; o[n * 4 + j] = mode == 0 ? gelu_tanh(v) : (mode == 1 ? v : sigmoidf_(v)); }
;                     if (mode == 2) { unsigned w0 = 0u, w1 = 0u;
; #pragma unroll
;                         for (int j = 0; j < 4; ++j) { w0 = __builtin_amdgcn_cvt_pk_u8_f32(fmaxf(o[j] * 255.f, 1.f), j, w0); w1 = __builtin_amdgcn_cvt_pk_u8_f32(fmaxf(o[4 + j] * 255.f, 1.f), j, w1); }
;                         u32x2 wv; wv.x = w0; wv.y = w1; *(u32x2*)(gates + row * 4096 + (c0 - 5120)) = wv; }
;                     else if (c0 < PLD) *(u32x4*)(proj + row * PLD + c0) = pack8(o); } }
	v_exp_f32_e32 v160, v160
	v_exp_f32_e32 v161, v161
	v_exp_f32_e32 v162, v162
	v_exp_f32_e32 v163, v163
	v_add_f32_e32 v156, 1.0, v156
	v_add_f32_e32 v157, 1.0, v157
	v_add_f32_e32 v158, 1.0, v158
	v_add_f32_e32 v159, 1.0, v159
	v_add_f32_e32 v160, 1.0, v160
	v_add_f32_e32 v161, 1.0, v161
	v_add_f32_e32 v162, 1.0, v162
	v_add_f32_e32 v163, 1.0, v163
	v_rcp_f32_e32 v156, v156
	v_rcp_f32_e32 v157, v157
	v_rcp_f32_e32 v158, v158
	v_rcp_f32_e32 v159, v159
	v_rcp_f32_e32 v160, v160
	v_rcp_f32_e32 v161, v161
	v_rcp_f32_e32 v162, v162
	v_rcp_f32_e32 v163, v163
	v_mul_f32_e32 v118, v118, v156
	v_mul_f32_e32 v119, v119, v157
	v_mul_f32_e32 v120, v120, v158
	v_mul_f32_e32 v121, v121, v159
	v_mul_f32_e32 v114, v114, v160
	v_mul_f32_e32 v115, v115, v161
	v_mul_f32_e32 v116, v116, v162
	v_mul_f32_e32 v117, v117, v163
	v_cvt_pk_bf16_f32 v168, v118, v119
	v_cvt_pk_bf16_f32 v169, v120, v121
	v_cvt_pk_bf16_f32 v170, v114, v115
	v_cvt_pk_bf16_f32 v171, v116, v117
	s_mov_b64 exec, s[100:101]
	global_store_dwordx4 v153, v[168:171], s[68:69] offset:256
	s_mov_b64 exec, -1
	v_mul_f32_e32 v110, v110, v147
	v_mul_f32_e32 v111, v111, v147
	v_mul_f32_e32 v112, v112, v147
	v_mul_f32_e32 v113, v113, v147
	v_mul_f32_e32 v106, v106, v147
	v_mul_f32_e32 v107, v107, v147
	v_mul_f32_e32 v108, v108, v147
	v_mul_f32_e32 v109, v109, v147
	v_mul_f32_e32 v156, s2, v110
	v_mul_f32_e32 v157, s2, v111
	v_mul_f32_e32 v158, s2, v112
	v_mul_f32_e32 v159, s2, v113
	v_mul_f32_e32 v160, s2, v106
	v_mul_f32_e32 v161, s2, v107
	v_mul_f32_e32 v162, s2, v108
	v_mul_f32_e32 v163, s2, v109
	v_mul_f32_e32 v156, v110, v156
	v_mul_f32_e32 v157, v111, v157
	v_mul_f32_e32 v158, v112, v158
	v_mul_f32_e32 v159, v113, v159
	v_mul_f32_e32 v160, v106, v160
	v_mul_f32_e32 v161, v107, v161
	v_mul_f32_e32 v162, v108, v162
	v_mul_f32_e32 v163, v109, v163
	v_fma_f32 v156, v110, v156, v110
	v_fma_f32 v157, v111, v157, v111
	v_fma_f32 v158, v112, v158, v112
	v_fma_f32 v159, v113, v159, v113
	v_fma_f32 v160, v106, v160, v106
	v_fma_f32 v161, v107, v161, v107
	v_fma_f32 v162, v108, v162, v108
	v_fma_f32 v163, v109, v163, v109
	v_mul_f32_e32 v156, s3, v156
	v_mul_f32_e32 v157, s3, v157
	v_mul_f32_e32 v158, s3, v158
	v_mul_f32_e32 v159, s3, v159
	v_mul_f32_e32 v160, s3, v160
	v_mul_f32_e32 v161, s3, v161
	v_mul_f32_e32 v162, s3, v162
	v_mul_f32_e32 v163, s3, v163
	v_mul_f32_e32 v156, -2.0, v156
	v_mul_f32_e32 v157, -2.0, v157
	v_mul_f32_e32 v158, -2.0, v158
	v_mul_f32_e32 v159, -2.0, v159
	v_mul_f32_e32 v160, -2.0, v160
	v_mul_f32_e32 v161, -2.0, v161
	v_mul_f32_e32 v162, -2.0, v162
	v_mul_f32_e32 v163, -2.0, v163
	v_mul_f32_e32 v156, s28, v156
	v_mul_f32_e32 v157, s28, v157
	v_mul_f32_e32 v158, s28, v158
	v_mul_f32_e32 v159, s28, v159
	v_mul_f32_e32 v160, s28, v160
	v_mul_f32_e32 v161, s28, v161
	v_mul_f32_e32 v162, s28, v162
	v_mul_f32_e32 v163, s28, v163
	v_exp_f32_e32 v156, v156
	v_exp_f32_e32 v157, v157
	v_exp_f32_e32 v158, v158
	v_exp_f32_e32 v159, v159
	v_exp_f32_e32 v160, v160
	v_exp_f32_e32 v161, v161
	v_exp_f32_e32 v162, v162
	v_exp_f32_e32 v163, v163
	v_add_f32_e32 v156, 1.0, v156
	v_add_f32_e32 v157, 1.0, v157
	v_add_f32_e32 v158, 1.0, v158
	v_add_f32_e32 v159, 1.0, v159
	v_add_f32_e32 v160, 1.0, v160
	v_add_f32_e32 v161, 1.0, v161
	v_add_f32_e32 v162, 1.0, v162
	v_add_f32_e32 v163, 1.0, v163
	v_rcp_f32_e32 v156, v156
	v_rcp_f32_e32 v157, v157
	v_rcp_f32_e32 v158, v158
	v_rcp_f32_e32 v159, v159
	v_rcp_f32_e32 v160, v160
	v_rcp_f32_e32 v161, v161
	v_rcp_f32_e32 v162, v162
	v_rcp_f32_e32 v163, v163
	v_mul_f32_e32 v110, v110, v156
	v_mul_f32_e32 v111, v111, v157
	v_mul_f32_e32 v112, v112, v158
	v_mul_f32_e32 v113, v113, v159
	v_mul_f32_e32 v106, v106, v160
	v_mul_f32_e32 v107, v107, v161
	v_mul_f32_e32 v108, v108, v162
	v_mul_f32_e32 v109, v109, v163
	v_add_u32_e32 v153, 0x26400, v153
	v_cvt_pk_bf16_f32 v164, v110, v111
	v_cvt_pk_bf16_f32 v165, v112, v113
	v_cvt_pk_bf16_f32 v166, v106, v107
	v_cvt_pk_bf16_f32 v167, v108, v109
	s_mov_b64 exec, s[24:25]
	global_store_dwordx4 v153, v[164:167], s[68:69]
	s_mov_b64 exec, -1
	v_mul_f32_e32 v102, v102, v147
	v_mul_f32_e32 v103, v103, v147
	v_mul_f32_e32 v104, v104, v147
	v_mul_f32_e32 v105, v105, v147
	v_mul_f32_e32 v98, v98, v147
	v_mul_f32_e32 v99, v99, v147
	v_mul_f32_e32 v100, v100, v147
	v_mul_f32_e32 v101, v101, v147
	v_mul_f32_e32 v156, s2, v102
	v_mul_f32_e32 v157, s2, v103
	v_mul_f32_e32 v158, s2, v104
	v_mul_f32_e32 v159, s2, v105
	v_mul_f32_e32 v160, s2, v98
	v_mul_f32_e32 v161, s2, v99
	v_mul_f32_e32 v162, s2, v100
	v_mul_f32_e32 v163, s2, v101
	v_mul_f32_e32 v156, v102, v156
	v_mul_f32_e32 v157, v103, v157
	v_mul_f32_e32 v158, v104, v158
	v_mul_f32_e32 v159, v105, v159
	v_mul_f32_e32 v160, v98, v160
	v_mul_f32_e32 v161, v99, v161
	v_mul_f32_e32 v162, v100, v162
	v_mul_f32_e32 v163, v101, v163
	v_fma_f32 v156, v102, v156, v102
	v_fma_f32 v157, v103, v157, v103
	v_fma_f32 v158, v104, v158, v104
	v_fma_f32 v159, v105, v159, v105
	v_fma_f32 v160, v98, v160, v98
	v_fma_f32 v161, v99, v161, v99
	v_fma_f32 v162, v100, v162, v100
	v_fma_f32 v163, v101, v163, v101
	v_mul_f32_e32 v156, s3, v156
	v_mul_f32_e32 v157, s3, v157
	v_mul_f32_e32 v158, s3, v158
	v_mul_f32_e32 v159, s3, v159
	v_mul_f32_e32 v160, s3, v160
	v_mul_f32_e32 v161, s3, v161
	v_mul_f32_e32 v162, s3, v162
	v_mul_f32_e32 v163, s3, v163
	v_mul_f32_e32 v156, -2.0, v156
	v_mul_f32_e32 v157, -2.0, v157
	v_mul_f32_e32 v158, -2.0, v158
	v_mul_f32_e32 v159, -2.0, v159
	v_mul_f32_e32 v160, -2.0, v160
	v_mul_f32_e32 v161, -2.0, v161
	v_mul_f32_e32 v162, -2.0, v162
	v_mul_f32_e32 v163, -2.0, v163
	v_mul_f32_e32 v156, s28, v156
	v_mul_f32_e32 v157, s28, v157
	v_mul_f32_e32 v158, s28, v158
; __device__ __forceinline__ u32x4 pack8(const float* f) { u32x4 o; o.x = pk2(f[0], f[1]); o.y = pk2(f[2], f[3]); o.z = pk2(f[4], f[5]); o.w = pk2(f[6], f[7]); return o; }
; __device__ __forceinline__ float sigmoidf_(float x) { return rcpf(1.0f + __expf(-x)); }
; __device__ __forceinline__ float gelu_tanh(float v) { const float u = 0.7978845608f * (v + 0.044715f * v * v * v); return v * rcpf(1.0f + __expf(-2.0f * u)); }
;     __device__ __forceinline__ void operator()(const f32x4 (&acc)[2][2][4][2], const Unit& u, int wr, int wc, int fr, int fq) const {
;     ...
;             for (int m = 0; m < 4; ++m) { const size_t row = (size_t)(row0 + ai * HALF + m * 16); const float rs = rsv[ai][m];
; #pragma unroll
;                 for (int bj = 0; bj < 2; ++bj) { float o[8];
;                     const int c0 = u.pn * BM + bj * HALF + wc * 32 + 8 * fq;
; #pragma unroll
;                     for (int n = 0; n < 2; ++n)
; #pragma unroll
;                         for (int j = 0; j < 4; ++j) { const float v = acc[ai][bj][m][n][j] * rs; o[n * 4 + j] = mode == 0 ? gelu_tanh(v) : (mode == 1 ? v : sigmoidf_(v)); }
;                     if (mode == 2) { unsigned w0 = 0u, w1 = 0u;
; #pragma unroll
;                         for (int j = 0; j < 4; ++j) { w0 = __builtin_amdgcn_cvt_pk_u8_f32(fmaxf(o[j] * 255.f, 1.f), j, w0); w1 = __builtin_amdgcn_cvt_pk_u8_f32(fmaxf(o[4 + j] * 255.f, 1.f), j, w1); }
;                         u32x2 wv; wv.x = w0; wv.y = w1; *(u32x2*)(gates + row * 4096 + (c0 - 5120)) = wv; }
;                     else if (c0 < PLD) *(u32x4*)(proj + row * PLD + c0) = pack8(o); } }
	v_mul_f32_e32 v159, s28, v159
	v_mul_f32_e32 v160, s28, v160
	v_mul_f32_e32 v161, s28, v161
	v_mul_f32_e32 v162, s28, v162
	v_mul_f32_e32 v163, s28, v163
	v_exp_f32_e32 v156, v156
	v_exp_f32_e32 v157, v157
	v_exp_f32_e32 v158, v158
	v_exp_f32_e32 v159, v159
	v_exp_f32_e32 v160, v160
	v_exp_f32_e32 v161, v161
	v_exp_f32_e32 v162, v162
	v_exp_f32_e32 v163, v163
	v_add_f32_e32 v156, 1.0, v156
	v_add_f32_e32 v157, 1.0, v157
	v_add_f32_e32 v158, 1.0, v158
	v_add_f32_e32 v159, 1.0, v159
	v_add_f32_e32 v160, 1.0, v160
	v_add_f32_e32 v161, 1.0, v161
	v_add_f32_e32 v162, 1.0, v162
	v_add_f32_e32 v163, 1.0, v163
	v_rcp_f32_e32 v156, v156
	v_rcp_f32_e32 v157, v157
	v_rcp_f32_e32 v158, v158
	v_rcp_f32_e32 v159, v159
	v_rcp_f32_e32 v160, v160
	v_rcp_f32_e32 v161, v161
	v_rcp_f32_e32 v162, v162
	v_rcp_f32_e32 v163, v163
	v_mul_f32_e32 v102, v102, v156
	v_mul_f32_e32 v103, v103, v157
	v_mul_f32_e32 v104, v104, v158
	v_mul_f32_e32 v105, v105, v159
	v_mul_f32_e32 v98, v98, v160
	v_mul_f32_e32 v99, v99, v161
	v_mul_f32_e32 v100, v100, v162
	v_mul_f32_e32 v101, v101, v163
	v_cvt_pk_bf16_f32 v168, v102, v103
	v_cvt_pk_bf16_f32 v169, v104, v105
	v_cvt_pk_bf16_f32 v170, v98, v99
	v_cvt_pk_bf16_f32 v171, v100, v101
	s_mov_b64 exec, s[100:101]
	global_store_dwordx4 v153, v[168:171], s[68:69] offset:256
	s_mov_b64 exec, -1
	v_mul_f32_e32 v94, v94, v144
	v_mul_f32_e32 v95, v95, v144
	v_mul_f32_e32 v96, v96, v144
	v_mul_f32_e32 v97, v97, v144
	v_mul_f32_e32 v90, v90, v144
	v_mul_f32_e32 v91, v91, v144
	v_mul_f32_e32 v92, v92, v144
	v_mul_f32_e32 v93, v93, v144
	v_mul_f32_e32 v156, s2, v94
	v_mul_f32_e32 v157, s2, v95
	v_mul_f32_e32 v158, s2, v96
	v_mul_f32_e32 v159, s2, v97
	v_mul_f32_e32 v160, s2, v90
	v_mul_f32_e32 v161, s2, v91
	v_mul_f32_e32 v162, s2, v92
	v_mul_f32_e32 v163, s2, v93
	v_mul_f32_e32 v156, v94, v156
	v_mul_f32_e32 v157, v95, v157
	v_mul_f32_e32 v158, v96, v158
	v_mul_f32_e32 v159, v97, v159
	v_mul_f32_e32 v160, v90, v160
	v_mul_f32_e32 v161, v91, v161
	v_mul_f32_e32 v162, v92, v162
	v_mul_f32_e32 v163, v93, v163
	v_fma_f32 v156, v94, v156, v94
	v_fma_f32 v157, v95, v157, v95
	v_fma_f32 v158, v96, v158, v96
	v_fma_f32 v159, v97, v159, v97
	v_fma_f32 v160, v90, v160, v90
	v_fma_f32 v161, v91, v161, v91
	v_fma_f32 v162, v92, v162, v92
	v_fma_f32 v163, v93, v163, v93
	v_mul_f32_e32 v156, s3, v156
	v_mul_f32_e32 v157, s3, v157
	v_mul_f32_e32 v158, s3, v158
	v_mul_f32_e32 v159, s3, v159
	v_mul_f32_e32 v160, s3, v160
	v_mul_f32_e32 v161, s3, v161
	v_mul_f32_e32 v162, s3, v162
	v_mul_f32_e32 v163, s3, v163
	v_mul_f32_e32 v156, -2.0, v156
	v_mul_f32_e32 v157, -2.0, v157
	v_mul_f32_e32 v158, -2.0, v158
	v_mul_f32_e32 v159, -2.0, v159
	v_mul_f32_e32 v160, -2.0, v160
	v_mul_f32_e32 v161, -2.0, v161
	v_mul_f32_e32 v162, -2.0, v162
	v_mul_f32_e32 v163, -2.0, v163
	v_mul_f32_e32 v156, s28, v156
	v_mul_f32_e32 v157, s28, v157
	v_mul_f32_e32 v158, s28, v158
	v_mul_f32_e32 v159, s28, v159
	v_mul_f32_e32 v160, s28, v160
	v_mul_f32_e32 v161, s28, v161
	v_mul_f32_e32 v162, s28, v162
	v_mul_f32_e32 v163, s28, v163
	v_exp_f32_e32 v156, v156
	v_exp_f32_e32 v157, v157
	v_exp_f32_e32 v158, v158
	v_exp_f32_e32 v159, v159
	v_exp_f32_e32 v160, v160
	v_exp_f32_e32 v161, v161
	v_exp_f32_e32 v162, v162
	v_exp_f32_e32 v163, v163
	v_add_f32_e32 v156, 1.0, v156
	v_add_f32_e32 v157, 1.0, v157
	v_add_f32_e32 v158, 1.0, v158
	v_add_f32_e32 v159, 1.0, v159
	v_add_f32_e32 v160, 1.0, v160
	v_add_f32_e32 v161, 1.0, v161
	v_add_f32_e32 v162, 1.0, v162
	v_add_f32_e32 v163, 1.0, v163
	v_rcp_f32_e32 v156, v156
	v_rcp_f32_e32 v157, v157
	v_rcp_f32_e32 v158, v158
	v_rcp_f32_e32 v159, v159
	v_rcp_f32_e32 v160, v160
	v_rcp_f32_e32 v161, v161
	v_rcp_f32_e32 v162, v162
	v_rcp_f32_e32 v163, v163
	v_mul_f32_e32 v94, v94, v156
	v_mul_f32_e32 v95, v95, v157
	v_mul_f32_e32 v96, v96, v158
	v_mul_f32_e32 v97, v97, v159
	v_mul_f32_e32 v90, v90, v160
	v_mul_f32_e32 v91, v91, v161
	v_mul_f32_e32 v92, v92, v162
	v_mul_f32_e32 v93, v93, v163
	v_add_u32_e32 v153, 0x26400, v153
	v_cvt_pk_bf16_f32 v164, v94, v95
	v_cvt_pk_bf16_f32 v165, v96, v97
	v_cvt_pk_bf16_f32 v166, v90, v91
	v_cvt_pk_bf16_f32 v167, v92, v93
	s_mov_b64 exec, s[24:25]
	global_store_dwordx4 v153, v[164:167], s[68:69]
	s_mov_b64 exec, -1
	v_mul_f32_e32 v86, v86, v144
	v_mul_f32_e32 v87, v87, v144
	v_mul_f32_e32 v88, v88, v144
	v_mul_f32_e32 v89, v89, v144
	v_mul_f32_e32 v82, v82, v144
	v_mul_f32_e32 v83, v83, v144
	v_mul_f32_e32 v84, v84, v144
	v_mul_f32_e32 v85, v85, v144
	v_mul_f32_e32 v156, s2, v86
	v_mul_f32_e32 v157, s2, v87
	v_mul_f32_e32 v158, s2, v88
	v_mul_f32_e32 v159, s2, v89
	v_mul_f32_e32 v160, s2, v82
	v_mul_f32_e32 v161, s2, v83
	v_mul_f32_e32 v162, s2, v84
	v_mul_f32_e32 v163, s2, v85
	v_mul_f32_e32 v156, v86, v156
	v_mul_f32_e32 v157, v87, v157
	v_mul_f32_e32 v158, v88, v158
	v_mul_f32_e32 v159, v89, v159
	v_mul_f32_e32 v160, v82, v160
	v_mul_f32_e32 v161, v83, v161
	v_mul_f32_e32 v162, v84, v162
	v_mul_f32_e32 v163, v85, v163
	v_fma_f32 v156, v86, v156, v86
	v_fma_f32 v157, v87, v157, v87
	v_fma_f32 v158, v88, v158, v88
	v_fma_f32 v159, v89, v159, v89
	v_fma_f32 v160, v82, v160, v82
	v_fma_f32 v161, v83, v161, v83
	v_fma_f32 v162, v84, v162, v84
	v_fma_f32 v163, v85, v163, v85
	v_mul_f32_e32 v156, s3, v156
	v_mul_f32_e32 v157, s3, v157
	v_mul_f32_e32 v158, s3, v158
	v_mul_f32_e32 v159, s3, v159
	v_mul_f32_e32 v160, s3, v160
	v_mul_f32_e32 v161, s3, v161
	v_mul_f32_e32 v162, s3, v162
	v_mul_f32_e32 v163, s3, v163
	v_mul_f32_e32 v156, -2.0, v156
	v_mul_f32_e32 v157, -2.0, v157
	v_mul_f32_e32 v158, -2.0, v158
	v_mul_f32_e32 v159, -2.0, v159
	v_mul_f32_e32 v160, -2.0, v160
	v_mul_f32_e32 v161, -2.0, v161
	v_mul_f32_e32 v162, -2.0, v162
; __device__ __forceinline__ u32x4 pack8(const float* f) { u32x4 o; o.x = pk2(f[0], f[1]); o.y = pk2(f[2], f[3]); o.z = pk2(f[4], f[5]); o.w = pk2(f[6], f[7]); return o; }
; __device__ __forceinline__ float sigmoidf_(float x) { return rcpf(1.0f + __expf(-x)); }
; __device__ __forceinline__ float gelu_tanh(float v) { const float u = 0.7978845608f * (v + 0.044715f * v * v * v); return v * rcpf(1.0f + __expf(-2.0f * u)); }
;     __device__ __forceinline__ void operator()(const f32x4 (&acc)[2][2][4][2], const Unit& u, int wr, int wc, int fr, int fq) const {
;     ...
;             for (int m = 0; m < 4; ++m) { const size_t row = (size_t)(row0 + ai * HALF + m * 16); const float rs = rsv[ai][m];
; #pragma unroll
;                 for (int bj = 0; bj < 2; ++bj) { float o[8];
;                     const int c0 = u.pn * BM + bj * HALF + wc * 32 + 8 * fq;
; #pragma unroll
;                     for (int n = 0; n < 2; ++n)
; #pragma unroll
;                         for (int j = 0; j < 4; ++j) { const float v = acc[ai][bj][m][n][j] * rs; o[n * 4 + j] = mode == 0 ? gelu_tanh(v) : (mode == 1 ? v : sigmoidf_(v)); }
;                     if (mode == 2) { unsigned w0 = 0u, w1 = 0u;
; #pragma unroll
;                         for (int j = 0; j < 4; ++j) { w0 = __builtin_amdgcn_cvt_pk_u8_f32(fmaxf(o[j] * 255.f, 1.f), j, w0); w1 = __builtin_amdgcn_cvt_pk_u8_f32(fmaxf(o[4 + j] * 255.f, 1.f), j, w1); }
;                         u32x2 wv; wv.x = w0; wv.y = w1; *(u32x2*)(gates + row * 4096 + (c0 - 5120)) = wv; }
;                     else if (c0 < PLD) *(u32x4*)(proj + row * PLD + c0) = pack8(o); } }
	v_mul_f32_e32 v163, -2.0, v163
	v_mul_f32_e32 v156, s28, v156
	v_mul_f32_e32 v157, s28, v157
	v_mul_f32_e32 v158, s28, v158
	v_mul_f32_e32 v159, s28, v159
	v_mul_f32_e32 v160, s28, v160
	v_mul_f32_e32 v161, s28, v161
	v_mul_f32_e32 v162, s28, v162
	v_mul_f32_e32 v163, s28, v163
	v_exp_f32_e32 v156, v156
	v_exp_f32_e32 v157, v157
	v_exp_f32_e32 v158, v158
	v_exp_f32_e32 v159, v159
	v_exp_f32_e32 v160, v160
	v_exp_f32_e32 v161, v161
	v_exp_f32_e32 v162, v162
	v_exp_f32_e32 v163, v163
	v_add_f32_e32 v156, 1.0, v156
	v_add_f32_e32 v157, 1.0, v157
	v_add_f32_e32 v158, 1.0, v158
	v_add_f32_e32 v159, 1.0, v159
	v_add_f32_e32 v160, 1.0, v160
	v_add_f32_e32 v161, 1.0, v161
	v_add_f32_e32 v162, 1.0, v162
	v_add_f32_e32 v163, 1.0, v163
	v_rcp_f32_e32 v156, v156
	v_rcp_f32_e32 v157, v157
	v_rcp_f32_e32 v158, v158
	v_rcp_f32_e32 v159, v159
	v_rcp_f32_e32 v160, v160
	v_rcp_f32_e32 v161, v161
	v_rcp_f32_e32 v162, v162
	v_rcp_f32_e32 v163, v163
	v_mul_f32_e32 v86, v86, v156
	v_mul_f32_e32 v87, v87, v157
	v_mul_f32_e32 v88, v88, v158
	v_mul_f32_e32 v89, v89, v159
	v_mul_f32_e32 v82, v82, v160
	v_mul_f32_e32 v83, v83, v161
	v_mul_f32_e32 v84, v84, v162
	v_mul_f32_e32 v85, v85, v163
	v_cvt_pk_bf16_f32 v168, v86, v87
	v_cvt_pk_bf16_f32 v169, v88, v89
	v_cvt_pk_bf16_f32 v170, v82, v83
	v_cvt_pk_bf16_f32 v171, v84, v85
	s_mov_b64 exec, s[100:101]
	global_store_dwordx4 v153, v[168:171], s[68:69] offset:256
	s_mov_b64 exec, -1
	v_mul_f32_e32 v78, v78, v145
	v_mul_f32_e32 v79, v79, v145
	v_mul_f32_e32 v80, v80, v145
	v_mul_f32_e32 v81, v81, v145
	v_mul_f32_e32 v74, v74, v145
	v_mul_f32_e32 v75, v75, v145
	v_mul_f32_e32 v76, v76, v145
	v_mul_f32_e32 v77, v77, v145
	v_mul_f32_e32 v156, s2, v78
	v_mul_f32_e32 v157, s2, v79
	v_mul_f32_e32 v158, s2, v80
	v_mul_f32_e32 v159, s2, v81
	v_mul_f32_e32 v160, s2, v74
	v_mul_f32_e32 v161, s2, v75
	v_mul_f32_e32 v162, s2, v76
	v_mul_f32_e32 v163, s2, v77
	v_mul_f32_e32 v156, v78, v156
	v_mul_f32_e32 v157, v79, v157
	v_mul_f32_e32 v158, v80, v158
	v_mul_f32_e32 v159, v81, v159
	v_mul_f32_e32 v160, v74, v160
	v_mul_f32_e32 v161, v75, v161
	v_mul_f32_e32 v162, v76, v162
	v_mul_f32_e32 v163, v77, v163
	v_fma_f32 v156, v78, v156, v78
	v_fma_f32 v157, v79, v157, v79
	v_fma_f32 v158, v80, v158, v80
	v_fma_f32 v159, v81, v159, v81
	v_fma_f32 v160, v74, v160, v74
	v_fma_f32 v161, v75, v161, v75
	v_fma_f32 v162, v76, v162, v76
	v_fma_f32 v163, v77, v163, v77
	v_mul_f32_e32 v156, s3, v156
	v_mul_f32_e32 v157, s3, v157
	v_mul_f32_e32 v158, s3, v158
	v_mul_f32_e32 v159, s3, v159
	v_mul_f32_e32 v160, s3, v160
	v_mul_f32_e32 v161, s3, v161
	v_mul_f32_e32 v162, s3, v162
	v_mul_f32_e32 v163, s3, v163
	v_mul_f32_e32 v156, -2.0, v156
	v_mul_f32_e32 v157, -2.0, v157
	v_mul_f32_e32 v158, -2.0, v158
	v_mul_f32_e32 v159, -2.0, v159
	v_mul_f32_e32 v160, -2.0, v160
	v_mul_f32_e32 v161, -2.0, v161
	v_mul_f32_e32 v162, -2.0, v162
	v_mul_f32_e32 v163, -2.0, v163
	v_mul_f32_e32 v156, s28, v156
	v_mul_f32_e32 v157, s28, v157
	v_mul_f32_e32 v158, s28, v158
	v_mul_f32_e32 v159, s28, v159
	v_mul_f32_e32 v160, s28, v160
	v_mul_f32_e32 v161, s28, v161
	v_mul_f32_e32 v162, s28, v162
	v_mul_f32_e32 v163, s28, v163
	v_exp_f32_e32 v156, v156
	v_exp_f32_e32 v157, v157
	v_exp_f32_e32 v158, v158
	v_exp_f32_e32 v159, v159
	v_exp_f32_e32 v160, v160
	v_exp_f32_e32 v161, v161
	v_exp_f32_e32 v162, v162
	v_exp_f32_e32 v163, v163
	v_add_f32_e32 v156, 1.0, v156
	v_add_f32_e32 v157, 1.0, v157
	v_add_f32_e32 v158, 1.0, v158
	v_add_f32_e32 v159, 1.0, v159
	v_add_f32_e32 v160, 1.0, v160
	v_add_f32_e32 v161, 1.0, v161
	v_add_f32_e32 v162, 1.0, v162
	v_add_f32_e32 v163, 1.0, v163
	v_rcp_f32_e32 v156, v156
	v_rcp_f32_e32 v157, v157
	v_rcp_f32_e32 v158, v158
	v_rcp_f32_e32 v159, v159
	v_rcp_f32_e32 v160, v160
	v_rcp_f32_e32 v161, v161
	v_rcp_f32_e32 v162, v162
	v_rcp_f32_e32 v163, v163
	v_mul_f32_e32 v78, v78, v156
	v_mul_f32_e32 v79, v79, v157
	v_mul_f32_e32 v80, v80, v158
	v_mul_f32_e32 v81, v81, v159
	v_mul_f32_e32 v74, v74, v160
	v_mul_f32_e32 v75, v75, v161
	v_mul_f32_e32 v76, v76, v162
	v_mul_f32_e32 v77, v77, v163
	v_add_u32_e32 v153, 0x26400, v153
	v_cvt_pk_bf16_f32 v164, v78, v79
	v_cvt_pk_bf16_f32 v165, v80, v81
	v_cvt_pk_bf16_f32 v166, v74, v75
	v_cvt_pk_bf16_f32 v167, v76, v77
	s_mov_b64 exec, s[24:25]
	global_store_dwordx4 v153, v[164:167], s[68:69]
	s_mov_b64 exec, -1
	v_mul_f32_e32 v70, v70, v145
	v_mul_f32_e32 v71, v71, v145
	v_mul_f32_e32 v72, v72, v145
	v_mul_f32_e32 v73, v73, v145
	v_mul_f32_e32 v66, v66, v145
	v_mul_f32_e32 v67, v67, v145
	v_mul_f32_e32 v68, v68, v145
	v_mul_f32_e32 v69, v69, v145
	v_mul_f32_e32 v156, s2, v70
	v_mul_f32_e32 v157, s2, v71
	v_mul_f32_e32 v158, s2, v72
	v_mul_f32_e32 v159, s2, v73
	v_mul_f32_e32 v160, s2, v66
	v_mul_f32_e32 v161, s2, v67
	v_mul_f32_e32 v162, s2, v68
	v_mul_f32_e32 v163, s2, v69
	v_mul_f32_e32 v156, v70, v156
	v_mul_f32_e32 v157, v71, v157
	v_mul_f32_e32 v158, v72, v158
	v_mul_f32_e32 v159, v73, v159
	v_mul_f32_e32 v160, v66, v160
	v_mul_f32_e32 v161, v67, v161
	v_mul_f32_e32 v162, v68, v162
	v_mul_f32_e32 v163, v69, v163
	v_fma_f32 v156, v70, v156, v70
	v_fma_f32 v157, v71, v157, v71
	v_fma_f32 v158, v72, v158, v72
	v_fma_f32 v159, v73, v159, v73
	v_fma_f32 v160, v66, v160, v66
	v_fma_f32 v161, v67, v161, v67
	v_fma_f32 v162, v68, v162, v68
	v_fma_f32 v163, v69, v163, v69
	v_mul_f32_e32 v156, s3, v156
	v_mul_f32_e32 v157, s3, v157
	v_mul_f32_e32 v158, s3, v158
	v_mul_f32_e32 v159, s3, v159
	v_mul_f32_e32 v160, s3, v160
	v_mul_f32_e32 v161, s3, v161
	v_mul_f32_e32 v162, s3, v162
	v_mul_f32_e32 v163, s3, v163
	v_mul_f32_e32 v156, -2.0, v156
	v_mul_f32_e32 v157, -2.0, v157
	v_mul_f32_e32 v158, -2.0, v158
; __device__ __forceinline__ u32x4 pack8(const float* f) { u32x4 o; o.x = pk2(f[0], f[1]); o.y = pk2(f[2], f[3]); o.z = pk2(f[4], f[5]); o.w = pk2(f[6], f[7]); return o; }
; __device__ __forceinline__ float sigmoidf_(float x) { return rcpf(1.0f + __expf(-x)); }
; __device__ __forceinline__ float gelu_tanh(float v) { const float u = 0.7978845608f * (v + 0.044715f * v * v * v); return v * rcpf(1.0f + __expf(-2.0f * u)); }
;     __device__ __forceinline__ void operator()(const f32x4 (&acc)[2][2][4][2], const Unit& u, int wr, int wc, int fr, int fq) const {
;     ...
;             for (int m = 0; m < 4; ++m) { const size_t row = (size_t)(row0 + ai * HALF + m * 16); const float rs = rsv[ai][m];
; #pragma unroll
;                 for (int bj = 0; bj < 2; ++bj) { float o[8];
;                     const int c0 = u.pn * BM + bj * HALF + wc * 32 + 8 * fq;
; #pragma unroll
;                     for (int n = 0; n < 2; ++n)
; #pragma unroll
;                         for (int j = 0; j < 4; ++j) { const float v = acc[ai][bj][m][n][j] * rs; o[n * 4 + j] = mode == 0 ? gelu_tanh(v) : (mode == 1 ? v : sigmoidf_(v)); }
;                     if (mode == 2) { unsigned w0 = 0u, w1 = 0u;
; #pragma unroll
;                         for (int j = 0; j < 4; ++j) { w0 = __builtin_amdgcn_cvt_pk_u8_f32(fmaxf(o[j] * 255.f, 1.f), j, w0); w1 = __builtin_amdgcn_cvt_pk_u8_f32(fmaxf(o[4 + j] * 255.f, 1.f), j, w1); }
;                         u32x2 wv; wv.x = w0; wv.y = w1; *(u32x2*)(gates + row * 4096 + (c0 - 5120)) = wv; }
;                     else if (c0 < PLD) *(u32x4*)(proj + row * PLD + c0) = pack8(o); } }
	v_mul_f32_e32 v159, -2.0, v159
	v_mul_f32_e32 v160, -2.0, v160
	v_mul_f32_e32 v161, -2.0, v161
	v_mul_f32_e32 v162, -2.0, v162
	v_mul_f32_e32 v163, -2.0, v163
	v_mul_f32_e32 v156, s28, v156
	v_mul_f32_e32 v157, s28, v157
	v_mul_f32_e32 v158, s28, v158
	v_mul_f32_e32 v159, s28, v159
	v_mul_f32_e32 v160, s28, v160
	v_mul_f32_e32 v161, s28, v161
	v_mul_f32_e32 v162, s28, v162
	v_mul_f32_e32 v163, s28, v163
	v_exp_f32_e32 v156, v156
	v_exp_f32_e32 v157, v157
	v_exp_f32_e32 v158, v158
	v_exp_f32_e32 v159, v159
	v_exp_f32_e32 v160, v160
	v_exp_f32_e32 v161, v161
	v_exp_f32_e32 v162, v162
	v_exp_f32_e32 v163, v163
	v_add_f32_e32 v156, 1.0, v156
	v_add_f32_e32 v157, 1.0, v157
	v_add_f32_e32 v158, 1.0, v158
	v_add_f32_e32 v159, 1.0, v159
	v_add_f32_e32 v160, 1.0, v160
	v_add_f32_e32 v161, 1.0, v161
	v_add_f32_e32 v162, 1.0, v162
	v_add_f32_e32 v163, 1.0, v163
	v_rcp_f32_e32 v156, v156
	v_rcp_f32_e32 v157, v157
	v_rcp_f32_e32 v158, v158
	v_rcp_f32_e32 v159, v159
	v_rcp_f32_e32 v160, v160
	v_rcp_f32_e32 v161, v161
	v_rcp_f32_e32 v162, v162
	v_rcp_f32_e32 v163, v163
	v_mul_f32_e32 v70, v70, v156
	v_mul_f32_e32 v71, v71, v157
	v_mul_f32_e32 v72, v72, v158
	v_mul_f32_e32 v73, v73, v159
	v_mul_f32_e32 v66, v66, v160
	v_mul_f32_e32 v67, v67, v161
	v_mul_f32_e32 v68, v68, v162
	v_mul_f32_e32 v69, v69, v163
	v_cvt_pk_bf16_f32 v168, v70, v71
	v_cvt_pk_bf16_f32 v169, v72, v73
	v_cvt_pk_bf16_f32 v170, v66, v67
	v_cvt_pk_bf16_f32 v171, v68, v69
	s_mov_b64 exec, s[100:101]
	global_store_dwordx4 v153, v[168:171], s[68:69] offset:256
	s_mov_b64 exec, -1
	v_mul_f32_e32 v62, v62, v142
	v_mul_f32_e32 v63, v63, v142
	v_mul_f32_e32 v64, v64, v142
	v_mul_f32_e32 v65, v65, v142
	v_mul_f32_e32 v58, v58, v142
	v_mul_f32_e32 v59, v59, v142
	v_mul_f32_e32 v60, v60, v142
	v_mul_f32_e32 v61, v61, v142
	v_mul_f32_e32 v156, s2, v62
	v_mul_f32_e32 v157, s2, v63
	v_mul_f32_e32 v158, s2, v64
	v_mul_f32_e32 v159, s2, v65
	v_mul_f32_e32 v160, s2, v58
	v_mul_f32_e32 v161, s2, v59
	v_mul_f32_e32 v162, s2, v60
	v_mul_f32_e32 v163, s2, v61
	v_mul_f32_e32 v156, v62, v156
	v_mul_f32_e32 v157, v63, v157
	v_mul_f32_e32 v158, v64, v158
	v_mul_f32_e32 v159, v65, v159
	v_mul_f32_e32 v160, v58, v160
	v_mul_f32_e32 v161, v59, v161
	v_mul_f32_e32 v162, v60, v162
	v_mul_f32_e32 v163, v61, v163
	v_fma_f32 v156, v62, v156, v62
	v_fma_f32 v157, v63, v157, v63
	v_fma_f32 v158, v64, v158, v64
	v_fma_f32 v159, v65, v159, v65
	v_fma_f32 v160, v58, v160, v58
	v_fma_f32 v161, v59, v161, v59
	v_fma_f32 v162, v60, v162, v60
	v_fma_f32 v163, v61, v163, v61
	v_mul_f32_e32 v156, s3, v156
	v_mul_f32_e32 v157, s3, v157
	v_mul_f32_e32 v158, s3, v158
	v_mul_f32_e32 v159, s3, v159
	v_mul_f32_e32 v160, s3, v160
	v_mul_f32_e32 v161, s3, v161
	v_mul_f32_e32 v162, s3, v162
	v_mul_f32_e32 v163, s3, v163
	v_mul_f32_e32 v156, -2.0, v156
	v_mul_f32_e32 v157, -2.0, v157
	v_mul_f32_e32 v158, -2.0, v158
	v_mul_f32_e32 v159, -2.0, v159
	v_mul_f32_e32 v160, -2.0, v160
	v_mul_f32_e32 v161, -2.0, v161
	v_mul_f32_e32 v162, -2.0, v162
	v_mul_f32_e32 v163, -2.0, v163
	v_mul_f32_e32 v156, s28, v156
	v_mul_f32_e32 v157, s28, v157
	v_mul_f32_e32 v158, s28, v158
	v_mul_f32_e32 v159, s28, v159
	v_mul_f32_e32 v160, s28, v160
	v_mul_f32_e32 v161, s28, v161
	v_mul_f32_e32 v162, s28, v162
	v_mul_f32_e32 v163, s28, v163
	v_exp_f32_e32 v156, v156
	v_exp_f32_e32 v157, v157
	v_exp_f32_e32 v158, v158
	v_exp_f32_e32 v159, v159
	v_exp_f32_e32 v160, v160
	v_exp_f32_e32 v161, v161
	v_exp_f32_e32 v162, v162
	v_exp_f32_e32 v163, v163
	v_add_f32_e32 v156, 1.0, v156
	v_add_f32_e32 v157, 1.0, v157
	v_add_f32_e32 v158, 1.0, v158
	v_add_f32_e32 v159, 1.0, v159
	v_add_f32_e32 v160, 1.0, v160
	v_add_f32_e32 v161, 1.0, v161
	v_add_f32_e32 v162, 1.0, v162
	v_add_f32_e32 v163, 1.0, v163
	v_rcp_f32_e32 v156, v156
	v_rcp_f32_e32 v157, v157
	v_rcp_f32_e32 v158, v158
	v_rcp_f32_e32 v159, v159
	v_rcp_f32_e32 v160, v160
	v_rcp_f32_e32 v161, v161
	v_rcp_f32_e32 v162, v162
	v_rcp_f32_e32 v163, v163
	v_mul_f32_e32 v62, v62, v156
	v_mul_f32_e32 v63, v63, v157
	v_mul_f32_e32 v64, v64, v158
	v_mul_f32_e32 v65, v65, v159
	v_mul_f32_e32 v58, v58, v160
	v_mul_f32_e32 v59, v59, v161
	v_mul_f32_e32 v60, v60, v162
	v_mul_f32_e32 v61, v61, v163
	v_add_u32_e32 v153, 0xbf400, v153
	v_cvt_pk_bf16_f32 v164, v62, v63
	v_cvt_pk_bf16_f32 v165, v64, v65
	v_cvt_pk_bf16_f32 v166, v58, v59
	v_cvt_pk_bf16_f32 v167, v60, v61
	s_mov_b64 exec, s[24:25]
	global_store_dwordx4 v153, v[164:167], s[68:69]
	s_mov_b64 exec, -1
	v_mul_f32_e32 v54, v54, v142
	v_mul_f32_e32 v55, v55, v142
	v_mul_f32_e32 v56, v56, v142
	v_mul_f32_e32 v57, v57, v142
	v_mul_f32_e32 v50, v50, v142
	v_mul_f32_e32 v51, v51, v142
	v_mul_f32_e32 v52, v52, v142
	v_mul_f32_e32 v53, v53, v142
	v_mul_f32_e32 v156, s2, v54
	v_mul_f32_e32 v157, s2, v55
	v_mul_f32_e32 v158, s2, v56
	v_mul_f32_e32 v159, s2, v57
	v_mul_f32_e32 v160, s2, v50
	v_mul_f32_e32 v161, s2, v51
	v_mul_f32_e32 v162, s2, v52
	v_mul_f32_e32 v163, s2, v53
	v_mul_f32_e32 v156, v54, v156
	v_mul_f32_e32 v157, v55, v157
	v_mul_f32_e32 v158, v56, v158
	v_mul_f32_e32 v159, v57, v159
	v_mul_f32_e32 v160, v50, v160
	v_mul_f32_e32 v161, v51, v161
	v_mul_f32_e32 v162, v52, v162
	v_mul_f32_e32 v163, v53, v163
	v_fma_f32 v156, v54, v156, v54
	v_fma_f32 v157, v55, v157, v55
	v_fma_f32 v158, v56, v158, v56
	v_fma_f32 v159, v57, v159, v57
	v_fma_f32 v160, v50, v160, v50
	v_fma_f32 v161, v51, v161, v51
	v_fma_f32 v162, v52, v162, v52
	v_fma_f32 v163, v53, v163, v53
	v_mul_f32_e32 v156, s3, v156
	v_mul_f32_e32 v157, s3, v157
	v_mul_f32_e32 v158, s3, v158
	v_mul_f32_e32 v159, s3, v159
	v_mul_f32_e32 v160, s3, v160
	v_mul_f32_e32 v161, s3, v161
	v_mul_f32_e32 v162, s3, v162
; __device__ __forceinline__ u32x4 pack8(const float* f) { u32x4 o; o.x = pk2(f[0], f[1]); o.y = pk2(f[2], f[3]); o.z = pk2(f[4], f[5]); o.w = pk2(f[6], f[7]); return o; }
; __device__ __forceinline__ float sigmoidf_(float x) { return rcpf(1.0f + __expf(-x)); }
; __device__ __forceinline__ float gelu_tanh(float v) { const float u = 0.7978845608f * (v + 0.044715f * v * v * v); return v * rcpf(1.0f + __expf(-2.0f * u)); }
;     __device__ __forceinline__ void operator()(const f32x4 (&acc)[2][2][4][2], const Unit& u, int wr, int wc, int fr, int fq) const {
;     ...
;             for (int m = 0; m < 4; ++m) { const size_t row = (size_t)(row0 + ai * HALF + m * 16); const float rs = rsv[ai][m];
; #pragma unroll
;                 for (int bj = 0; bj < 2; ++bj) { float o[8];
;                     const int c0 = u.pn * BM + bj * HALF + wc * 32 + 8 * fq;
; #pragma unroll
;                     for (int n = 0; n < 2; ++n)
; #pragma unroll
;                         for (int j = 0; j < 4; ++j) { const float v = acc[ai][bj][m][n][j] * rs; o[n * 4 + j] = mode == 0 ? gelu_tanh(v) : (mode == 1 ? v : sigmoidf_(v)); }
;                     if (mode == 2) { unsigned w0 = 0u, w1 = 0u;
; #pragma unroll
;                         for (int j = 0; j < 4; ++j) { w0 = __builtin_amdgcn_cvt_pk_u8_f32(fmaxf(o[j] * 255.f, 1.f), j, w0); w1 = __builtin_amdgcn_cvt_pk_u8_f32(fmaxf(o[4 + j] * 255.f, 1.f), j, w1); }
;                         u32x2 wv; wv.x = w0; wv.y = w1; *(u32x2*)(gates + row * 4096 + (c0 - 5120)) = wv; }
;                     else if (c0 < PLD) *(u32x4*)(proj + row * PLD + c0) = pack8(o); } }
	v_mul_f32_e32 v163, s3, v163
	v_mul_f32_e32 v156, -2.0, v156
	v_mul_f32_e32 v157, -2.0, v157
	v_mul_f32_e32 v158, -2.0, v158
	v_mul_f32_e32 v159, -2.0, v159
	v_mul_f32_e32 v160, -2.0, v160
	v_mul_f32_e32 v161, -2.0, v161
	v_mul_f32_e32 v162, -2.0, v162
	v_mul_f32_e32 v163, -2.0, v163
	v_mul_f32_e32 v156, s28, v156
	v_mul_f32_e32 v157, s28, v157
	v_mul_f32_e32 v158, s28, v158
	v_mul_f32_e32 v159, s28, v159
	v_mul_f32_e32 v160, s28, v160
	v_mul_f32_e32 v161, s28, v161
	v_mul_f32_e32 v162, s28, v162
	v_mul_f32_e32 v163, s28, v163
	v_exp_f32_e32 v156, v156
	v_exp_f32_e32 v157, v157
	v_exp_f32_e32 v158, v158
	v_exp_f32_e32 v159, v159
	v_exp_f32_e32 v160, v160
	v_exp_f32_e32 v161, v161
	v_exp_f32_e32 v162, v162
	v_exp_f32_e32 v163, v163
	v_add_f32_e32 v156, 1.0, v156
	v_add_f32_e32 v157, 1.0, v157
	v_add_f32_e32 v158, 1.0, v158
	v_add_f32_e32 v159, 1.0, v159
	v_add_f32_e32 v160, 1.0, v160
	v_add_f32_e32 v161, 1.0, v161
	v_add_f32_e32 v162, 1.0, v162
	v_add_f32_e32 v163, 1.0, v163
	v_rcp_f32_e32 v156, v156
	v_rcp_f32_e32 v157, v157
	v_rcp_f32_e32 v158, v158
	v_rcp_f32_e32 v159, v159
	v_rcp_f32_e32 v160, v160
	v_rcp_f32_e32 v161, v161
	v_rcp_f32_e32 v162, v162
	v_rcp_f32_e32 v163, v163
	v_mul_f32_e32 v54, v54, v156
	v_mul_f32_e32 v55, v55, v157
	v_mul_f32_e32 v56, v56, v158
	v_mul_f32_e32 v57, v57, v159
	v_mul_f32_e32 v50, v50, v160
	v_mul_f32_e32 v51, v51, v161
	v_mul_f32_e32 v52, v52, v162
	v_mul_f32_e32 v53, v53, v163
	v_cvt_pk_bf16_f32 v168, v54, v55
	v_cvt_pk_bf16_f32 v169, v56, v57
	v_cvt_pk_bf16_f32 v170, v50, v51
	v_cvt_pk_bf16_f32 v171, v52, v53
	s_mov_b64 exec, s[100:101]
	global_store_dwordx4 v153, v[168:171], s[68:69] offset:256
	s_mov_b64 exec, -1
	v_mul_f32_e32 v46, v46, v143
	v_mul_f32_e32 v47, v47, v143
	v_mul_f32_e32 v48, v48, v143
	v_mul_f32_e32 v49, v49, v143
	v_mul_f32_e32 v42, v42, v143
	v_mul_f32_e32 v43, v43, v143
	v_mul_f32_e32 v44, v44, v143
	v_mul_f32_e32 v45, v45, v143
	v_mul_f32_e32 v156, s2, v46
	v_mul_f32_e32 v157, s2, v47
	v_mul_f32_e32 v158, s2, v48
	v_mul_f32_e32 v159, s2, v49
	v_mul_f32_e32 v160, s2, v42
	v_mul_f32_e32 v161, s2, v43
	v_mul_f32_e32 v162, s2, v44
	v_mul_f32_e32 v163, s2, v45
	v_mul_f32_e32 v156, v46, v156
	v_mul_f32_e32 v157, v47, v157
	v_mul_f32_e32 v158, v48, v158
	v_mul_f32_e32 v159, v49, v159
	v_mul_f32_e32 v160, v42, v160
	v_mul_f32_e32 v161, v43, v161
	v_mul_f32_e32 v162, v44, v162
	v_mul_f32_e32 v163, v45, v163
	v_fma_f32 v156, v46, v156, v46
	v_fma_f32 v157, v47, v157, v47
	v_fma_f32 v158, v48, v158, v48
	v_fma_f32 v159, v49, v159, v49
	v_fma_f32 v160, v42, v160, v42
	v_fma_f32 v161, v43, v161, v43
	v_fma_f32 v162, v44, v162, v44
	v_fma_f32 v163, v45, v163, v45
	v_mul_f32_e32 v156, s3, v156
	v_mul_f32_e32 v157, s3, v157
	v_mul_f32_e32 v158, s3, v158
	v_mul_f32_e32 v159, s3, v159
	v_mul_f32_e32 v160, s3, v160
	v_mul_f32_e32 v161, s3, v161
	v_mul_f32_e32 v162, s3, v162
	v_mul_f32_e32 v163, s3, v163
	v_mul_f32_e32 v156, -2.0, v156
	v_mul_f32_e32 v157, -2.0, v157
	v_mul_f32_e32 v158, -2.0, v158
	v_mul_f32_e32 v159, -2.0, v159
	v_mul_f32_e32 v160, -2.0, v160
	v_mul_f32_e32 v161, -2.0, v161
	v_mul_f32_e32 v162, -2.0, v162
	v_mul_f32_e32 v163, -2.0, v163
	v_mul_f32_e32 v156, s28, v156
	v_mul_f32_e32 v157, s28, v157
	v_mul_f32_e32 v158, s28, v158
	v_mul_f32_e32 v159, s28, v159
	v_mul_f32_e32 v160, s28, v160
	v_mul_f32_e32 v161, s28, v161
	v_mul_f32_e32 v162, s28, v162
	v_mul_f32_e32 v163, s28, v163
	v_exp_f32_e32 v156, v156
	v_exp_f32_e32 v157, v157
	v_exp_f32_e32 v158, v158
	v_exp_f32_e32 v159, v159
	v_exp_f32_e32 v160, v160
	v_exp_f32_e32 v161, v161
	v_exp_f32_e32 v162, v162
	v_exp_f32_e32 v163, v163
	v_add_f32_e32 v156, 1.0, v156
	v_add_f32_e32 v157, 1.0, v157
	v_add_f32_e32 v158, 1.0, v158
	v_add_f32_e32 v159, 1.0, v159
	v_add_f32_e32 v160, 1.0, v160
	v_add_f32_e32 v161, 1.0, v161
	v_add_f32_e32 v162, 1.0, v162
	v_add_f32_e32 v163, 1.0, v163
	v_rcp_f32_e32 v156, v156
	v_rcp_f32_e32 v157, v157
	v_rcp_f32_e32 v158, v158
	v_rcp_f32_e32 v159, v159
	v_rcp_f32_e32 v160, v160
	v_rcp_f32_e32 v161, v161
	v_rcp_f32_e32 v162, v162
	v_rcp_f32_e32 v163, v163
	v_mul_f32_e32 v46, v46, v156
	v_mul_f32_e32 v47, v47, v157
	v_mul_f32_e32 v48, v48, v158
	v_mul_f32_e32 v49, v49, v159
	v_mul_f32_e32 v42, v42, v160
	v_mul_f32_e32 v43, v43, v161
	v_mul_f32_e32 v44, v44, v162
	v_mul_f32_e32 v45, v45, v163
	v_add_u32_e32 v153, 0x26400, v153
	v_cvt_pk_bf16_f32 v164, v46, v47
	v_cvt_pk_bf16_f32 v165, v48, v49
	v_cvt_pk_bf16_f32 v166, v42, v43
	v_cvt_pk_bf16_f32 v167, v44, v45
	s_mov_b64 exec, s[24:25]
	global_store_dwordx4 v153, v[164:167], s[68:69]
	s_mov_b64 exec, -1
	v_mul_f32_e32 v38, v38, v143
	v_mul_f32_e32 v39, v39, v143
	v_mul_f32_e32 v40, v40, v143
	v_mul_f32_e32 v41, v41, v143
	v_mul_f32_e32 v34, v34, v143
	v_mul_f32_e32 v35, v35, v143
	v_mul_f32_e32 v36, v36, v143
	v_mul_f32_e32 v37, v37, v143
	v_mul_f32_e32 v156, s2, v38
	v_mul_f32_e32 v157, s2, v39
	v_mul_f32_e32 v158, s2, v40
	v_mul_f32_e32 v159, s2, v41
	v_mul_f32_e32 v160, s2, v34
	v_mul_f32_e32 v161, s2, v35
	v_mul_f32_e32 v162, s2, v36
	v_mul_f32_e32 v163, s2, v37
	v_mul_f32_e32 v156, v38, v156
	v_mul_f32_e32 v157, v39, v157
	v_mul_f32_e32 v158, v40, v158
	v_mul_f32_e32 v159, v41, v159
	v_mul_f32_e32 v160, v34, v160
	v_mul_f32_e32 v161, v35, v161
	v_mul_f32_e32 v162, v36, v162
	v_mul_f32_e32 v163, v37, v163
	v_fma_f32 v156, v38, v156, v38
	v_fma_f32 v157, v39, v157, v39
	v_fma_f32 v158, v40, v158, v40
	v_fma_f32 v159, v41, v159, v41
	v_fma_f32 v160, v34, v160, v34
	v_fma_f32 v161, v35, v161, v35
	v_fma_f32 v162, v36, v162, v36
	v_fma_f32 v163, v37, v163, v37
	v_mul_f32_e32 v156, s3, v156
	v_mul_f32_e32 v157, s3, v157
	v_mul_f32_e32 v158, s3, v158
; __device__ __forceinline__ u32x4 pack8(const float* f) { u32x4 o; o.x = pk2(f[0], f[1]); o.y = pk2(f[2], f[3]); o.z = pk2(f[4], f[5]); o.w = pk2(f[6], f[7]); return o; }
; __device__ __forceinline__ float sigmoidf_(float x) { return rcpf(1.0f + __expf(-x)); }
; __device__ __forceinline__ float gelu_tanh(float v) { const float u = 0.7978845608f * (v + 0.044715f * v * v * v); return v * rcpf(1.0f + __expf(-2.0f * u)); }
;     __device__ __forceinline__ void operator()(const f32x4 (&acc)[2][2][4][2], const Unit& u, int wr, int wc, int fr, int fq) const {
;     ...
;             for (int m = 0; m < 4; ++m) { const size_t row = (size_t)(row0 + ai * HALF + m * 16); const float rs = rsv[ai][m];
; #pragma unroll
;                 for (int bj = 0; bj < 2; ++bj) { float o[8];
;                     const int c0 = u.pn * BM + bj * HALF + wc * 32 + 8 * fq;
; #pragma unroll
;                     for (int n = 0; n < 2; ++n)
; #pragma unroll
;                         for (int j = 0; j < 4; ++j) { const float v = acc[ai][bj][m][n][j] * rs; o[n * 4 + j] = mode == 0 ? gelu_tanh(v) : (mode == 1 ? v : sigmoidf_(v)); }
;                     if (mode == 2) { unsigned w0 = 0u, w1 = 0u;
; #pragma unroll
;                         for (int j = 0; j < 4; ++j) { w0 = __builtin_amdgcn_cvt_pk_u8_f32(fmaxf(o[j] * 255.f, 1.f), j, w0); w1 = __builtin_amdgcn_cvt_pk_u8_f32(fmaxf(o[4 + j] * 255.f, 1.f), j, w1); }
;                         u32x2 wv; wv.x = w0; wv.y = w1; *(u32x2*)(gates + row * 4096 + (c0 - 5120)) = wv; }
;                     else if (c0 < PLD) *(u32x4*)(proj + row * PLD + c0) = pack8(o); } }
	v_mul_f32_e32 v159, s3, v159
	v_mul_f32_e32 v160, s3, v160
	v_mul_f32_e32 v161, s3, v161
	v_mul_f32_e32 v162, s3, v162
	v_mul_f32_e32 v163, s3, v163
	v_mul_f32_e32 v156, -2.0, v156
	v_mul_f32_e32 v157, -2.0, v157
	v_mul_f32_e32 v158, -2.0, v158
	v_mul_f32_e32 v159, -2.0, v159
	v_mul_f32_e32 v160, -2.0, v160
	v_mul_f32_e32 v161, -2.0, v161
	v_mul_f32_e32 v162, -2.0, v162
	v_mul_f32_e32 v163, -2.0, v163
	v_mul_f32_e32 v156, s28, v156
	v_mul_f32_e32 v157, s28, v157
	v_mul_f32_e32 v158, s28, v158
	v_mul_f32_e32 v159, s28, v159
	v_mul_f32_e32 v160, s28, v160
	v_mul_f32_e32 v161, s28, v161
	v_mul_f32_e32 v162, s28, v162
	v_mul_f32_e32 v163, s28, v163
	v_exp_f32_e32 v156, v156
	v_exp_f32_e32 v157, v157
	v_exp_f32_e32 v158, v158
	v_exp_f32_e32 v159, v159
	v_exp_f32_e32 v160, v160
	v_exp_f32_e32 v161, v161
	v_exp_f32_e32 v162, v162
	v_exp_f32_e32 v163, v163
	v_add_f32_e32 v156, 1.0, v156
	v_add_f32_e32 v157, 1.0, v157
	v_add_f32_e32 v158, 1.0, v158
	v_add_f32_e32 v159, 1.0, v159
	v_add_f32_e32 v160, 1.0, v160
	v_add_f32_e32 v161, 1.0, v161
	v_add_f32_e32 v162, 1.0, v162
	v_add_f32_e32 v163, 1.0, v163
	v_rcp_f32_e32 v156, v156
	v_rcp_f32_e32 v157, v157
	v_rcp_f32_e32 v158, v158
	v_rcp_f32_e32 v159, v159
	v_rcp_f32_e32 v160, v160
	v_rcp_f32_e32 v161, v161
	v_rcp_f32_e32 v162, v162
	v_rcp_f32_e32 v163, v163
	v_mul_f32_e32 v38, v38, v156
	v_mul_f32_e32 v39, v39, v157
	v_mul_f32_e32 v40, v40, v158
	v_mul_f32_e32 v41, v41, v159
	v_mul_f32_e32 v34, v34, v160
	v_mul_f32_e32 v35, v35, v161
	v_mul_f32_e32 v36, v36, v162
	v_mul_f32_e32 v37, v37, v163
	v_cvt_pk_bf16_f32 v168, v38, v39
	v_cvt_pk_bf16_f32 v169, v40, v41
	v_cvt_pk_bf16_f32 v170, v34, v35
	v_cvt_pk_bf16_f32 v171, v36, v37
	s_mov_b64 exec, s[100:101]
	global_store_dwordx4 v153, v[168:171], s[68:69] offset:256
	s_mov_b64 exec, -1
	v_mul_f32_e32 v30, v30, v140
	v_mul_f32_e32 v31, v31, v140
	v_mul_f32_e32 v32, v32, v140
	v_mul_f32_e32 v33, v33, v140
	v_mul_f32_e32 v26, v26, v140
	v_mul_f32_e32 v27, v27, v140
	v_mul_f32_e32 v28, v28, v140
	v_mul_f32_e32 v29, v29, v140
	v_mul_f32_e32 v156, s2, v30
	v_mul_f32_e32 v157, s2, v31
	v_mul_f32_e32 v158, s2, v32
	v_mul_f32_e32 v159, s2, v33
	v_mul_f32_e32 v160, s2, v26
	v_mul_f32_e32 v161, s2, v27
	v_mul_f32_e32 v162, s2, v28
	v_mul_f32_e32 v163, s2, v29
	v_mul_f32_e32 v156, v30, v156
	v_mul_f32_e32 v157, v31, v157
	v_mul_f32_e32 v158, v32, v158
	v_mul_f32_e32 v159, v33, v159
	v_mul_f32_e32 v160, v26, v160
	v_mul_f32_e32 v161, v27, v161
	v_mul_f32_e32 v162, v28, v162
	v_mul_f32_e32 v163, v29, v163
	v_fma_f32 v156, v30, v156, v30
	v_fma_f32 v157, v31, v157, v31
	v_fma_f32 v158, v32, v158, v32
	v_fma_f32 v159, v33, v159, v33
	v_fma_f32 v160, v26, v160, v26
	v_fma_f32 v161, v27, v161, v27
	v_fma_f32 v162, v28, v162, v28
	v_fma_f32 v163, v29, v163, v29
	v_mul_f32_e32 v156, s3, v156
	v_mul_f32_e32 v157, s3, v157
	v_mul_f32_e32 v158, s3, v158
	v_mul_f32_e32 v159, s3, v159
	v_mul_f32_e32 v160, s3, v160
	v_mul_f32_e32 v161, s3, v161
	v_mul_f32_e32 v162, s3, v162
	v_mul_f32_e32 v163, s3, v163
	v_mul_f32_e32 v156, -2.0, v156
	v_mul_f32_e32 v157, -2.0, v157
	v_mul_f32_e32 v158, -2.0, v158
	v_mul_f32_e32 v159, -2.0, v159
	v_mul_f32_e32 v160, -2.0, v160
	v_mul_f32_e32 v161, -2.0, v161
	v_mul_f32_e32 v162, -2.0, v162
	v_mul_f32_e32 v163, -2.0, v163
	v_mul_f32_e32 v156, s28, v156
	v_mul_f32_e32 v157, s28, v157
	v_mul_f32_e32 v158, s28, v158
	v_mul_f32_e32 v159, s28, v159
	v_mul_f32_e32 v160, s28, v160
	v_mul_f32_e32 v161, s28, v161
	v_mul_f32_e32 v162, s28, v162
	v_mul_f32_e32 v163, s28, v163
	v_exp_f32_e32 v156, v156
	v_exp_f32_e32 v157, v157
	v_exp_f32_e32 v158, v158
	v_exp_f32_e32 v159, v159
	v_exp_f32_e32 v160, v160
	v_exp_f32_e32 v161, v161
	v_exp_f32_e32 v162, v162
	v_exp_f32_e32 v163, v163
	v_add_f32_e32 v156, 1.0, v156
	v_add_f32_e32 v157, 1.0, v157
	v_add_f32_e32 v158, 1.0, v158
	v_add_f32_e32 v159, 1.0, v159
	v_add_f32_e32 v160, 1.0, v160
	v_add_f32_e32 v161, 1.0, v161
	v_add_f32_e32 v162, 1.0, v162
	v_add_f32_e32 v163, 1.0, v163
	v_rcp_f32_e32 v156, v156
	v_rcp_f32_e32 v157, v157
	v_rcp_f32_e32 v158, v158
	v_rcp_f32_e32 v159, v159
	v_rcp_f32_e32 v160, v160
	v_rcp_f32_e32 v161, v161
	v_rcp_f32_e32 v162, v162
	v_rcp_f32_e32 v163, v163
	v_mul_f32_e32 v30, v30, v156
	v_mul_f32_e32 v31, v31, v157
	v_mul_f32_e32 v32, v32, v158
	v_mul_f32_e32 v33, v33, v159
	v_mul_f32_e32 v26, v26, v160
	v_mul_f32_e32 v27, v27, v161
	v_mul_f32_e32 v28, v28, v162
	v_mul_f32_e32 v29, v29, v163
	v_add_u32_e32 v153, 0x26400, v153
	v_cvt_pk_bf16_f32 v164, v30, v31
	v_cvt_pk_bf16_f32 v165, v32, v33
	v_cvt_pk_bf16_f32 v166, v26, v27
	v_cvt_pk_bf16_f32 v167, v28, v29
	s_mov_b64 exec, s[24:25]
	global_store_dwordx4 v153, v[164:167], s[68:69]
	s_mov_b64 exec, -1
	v_mul_f32_e32 v22, v22, v140
	v_mul_f32_e32 v23, v23, v140
	v_mul_f32_e32 v24, v24, v140
	v_mul_f32_e32 v25, v25, v140
	v_mul_f32_e32 v18, v18, v140
	v_mul_f32_e32 v19, v19, v140
	v_mul_f32_e32 v20, v20, v140
	v_mul_f32_e32 v21, v21, v140
	v_mul_f32_e32 v156, s2, v22
	v_mul_f32_e32 v157, s2, v23
	v_mul_f32_e32 v158, s2, v24
	v_mul_f32_e32 v159, s2, v25
	v_mul_f32_e32 v160, s2, v18
	v_mul_f32_e32 v161, s2, v19
	v_mul_f32_e32 v162, s2, v20
	v_mul_f32_e32 v163, s2, v21
	v_mul_f32_e32 v156, v22, v156
	v_mul_f32_e32 v157, v23, v157
	v_mul_f32_e32 v158, v24, v158
	v_mul_f32_e32 v159, v25, v159
	v_mul_f32_e32 v160, v18, v160
	v_mul_f32_e32 v161, v19, v161
	v_mul_f32_e32 v162, v20, v162
	v_mul_f32_e32 v163, v21, v163
	v_fma_f32 v156, v22, v156, v22
	v_fma_f32 v157, v23, v157, v23
	v_fma_f32 v158, v24, v158, v24
	v_fma_f32 v159, v25, v159, v25
	v_fma_f32 v160, v18, v160, v18
	v_fma_f32 v161, v19, v161, v19
	v_fma_f32 v162, v20, v162, v20
; __device__ __forceinline__ u32x4 pack8(const float* f) { u32x4 o; o.x = pk2(f[0], f[1]); o.y = pk2(f[2], f[3]); o.z = pk2(f[4], f[5]); o.w = pk2(f[6], f[7]); return o; }
; __device__ __forceinline__ float sigmoidf_(float x) { return rcpf(1.0f + __expf(-x)); }
; __device__ __forceinline__ float gelu_tanh(float v) { const float u = 0.7978845608f * (v + 0.044715f * v * v * v); return v * rcpf(1.0f + __expf(-2.0f * u)); }
;     __device__ __forceinline__ void operator()(const f32x4 (&acc)[2][2][4][2], const Unit& u, int wr, int wc, int fr, int fq) const {
;     ...
;             for (int m = 0; m < 4; ++m) { const size_t row = (size_t)(row0 + ai * HALF + m * 16); const float rs = rsv[ai][m];
; #pragma unroll
;                 for (int bj = 0; bj < 2; ++bj) { float o[8];
;                     const int c0 = u.pn * BM + bj * HALF + wc * 32 + 8 * fq;
; #pragma unroll
;                     for (int n = 0; n < 2; ++n)
; #pragma unroll
;                         for (int j = 0; j < 4; ++j) { const float v = acc[ai][bj][m][n][j] * rs; o[n * 4 + j] = mode == 0 ? gelu_tanh(v) : (mode == 1 ? v : sigmoidf_(v)); }
;                     if (mode == 2) { unsigned w0 = 0u, w1 = 0u;
; #pragma unroll
;                         for (int j = 0; j < 4; ++j) { w0 = __builtin_amdgcn_cvt_pk_u8_f32(fmaxf(o[j] * 255.f, 1.f), j, w0); w1 = __builtin_amdgcn_cvt_pk_u8_f32(fmaxf(o[4 + j] * 255.f, 1.f), j, w1); }
;                         u32x2 wv; wv.x = w0; wv.y = w1; *(u32x2*)(gates + row * 4096 + (c0 - 5120)) = wv; }
;                     else if (c0 < PLD) *(u32x4*)(proj + row * PLD + c0) = pack8(o); } }
	v_fma_f32 v163, v21, v163, v21
	v_mul_f32_e32 v156, s3, v156
	v_mul_f32_e32 v157, s3, v157
	v_mul_f32_e32 v158, s3, v158
	v_mul_f32_e32 v159, s3, v159
	v_mul_f32_e32 v160, s3, v160
	v_mul_f32_e32 v161, s3, v161
	v_mul_f32_e32 v162, s3, v162
	v_mul_f32_e32 v163, s3, v163
	v_mul_f32_e32 v156, -2.0, v156
	v_mul_f32_e32 v157, -2.0, v157
	v_mul_f32_e32 v158, -2.0, v158
	v_mul_f32_e32 v159, -2.0, v159
	v_mul_f32_e32 v160, -2.0, v160
	v_mul_f32_e32 v161, -2.0, v161
	v_mul_f32_e32 v162, -2.0, v162
	v_mul_f32_e32 v163, -2.0, v163
	v_mul_f32_e32 v156, s28, v156
	v_mul_f32_e32 v157, s28, v157
	v_mul_f32_e32 v158, s28, v158
	v_mul_f32_e32 v159, s28, v159
	v_mul_f32_e32 v160, s28, v160
	v_mul_f32_e32 v161, s28, v161
	v_mul_f32_e32 v162, s28, v162
	v_mul_f32_e32 v163, s28, v163
	v_exp_f32_e32 v156, v156
	v_exp_f32_e32 v157, v157
	v_exp_f32_e32 v158, v158
	v_exp_f32_e32 v159, v159
	v_exp_f32_e32 v160, v160
	v_exp_f32_e32 v161, v161
	v_exp_f32_e32 v162, v162
	v_exp_f32_e32 v163, v163
	v_add_f32_e32 v156, 1.0, v156
	v_add_f32_e32 v157, 1.0, v157
	v_add_f32_e32 v158, 1.0, v158
	v_add_f32_e32 v159, 1.0, v159
	v_add_f32_e32 v160, 1.0, v160
	v_add_f32_e32 v161, 1.0, v161
	v_add_f32_e32 v162, 1.0, v162
	v_add_f32_e32 v163, 1.0, v163
	v_rcp_f32_e32 v156, v156
	v_rcp_f32_e32 v157, v157
	v_rcp_f32_e32 v158, v158
	v_rcp_f32_e32 v159, v159
	v_rcp_f32_e32 v160, v160
	v_rcp_f32_e32 v161, v161
	v_rcp_f32_e32 v162, v162
	v_rcp_f32_e32 v163, v163
	v_mul_f32_e32 v22, v22, v156
	v_mul_f32_e32 v23, v23, v157
	v_mul_f32_e32 v24, v24, v158
	v_mul_f32_e32 v25, v25, v159
	v_mul_f32_e32 v18, v18, v160
	v_mul_f32_e32 v19, v19, v161
	v_mul_f32_e32 v20, v20, v162
	v_mul_f32_e32 v21, v21, v163
	v_cvt_pk_bf16_f32 v168, v22, v23
	v_cvt_pk_bf16_f32 v169, v24, v25
	v_cvt_pk_bf16_f32 v170, v18, v19
	v_cvt_pk_bf16_f32 v171, v20, v21
	s_mov_b64 exec, s[100:101]
	global_store_dwordx4 v153, v[168:171], s[68:69] offset:256
	s_mov_b64 exec, -1
	v_mul_f32_e32 v14, v14, v141
	v_mul_f32_e32 v15, v15, v141
	v_mul_f32_e32 v16, v16, v141
	v_mul_f32_e32 v17, v17, v141
	v_mul_f32_e32 v10, v10, v141
	v_mul_f32_e32 v11, v11, v141
	v_mul_f32_e32 v12, v12, v141
	v_mul_f32_e32 v13, v13, v141
	v_mul_f32_e32 v156, s2, v14
	v_mul_f32_e32 v157, s2, v15
	v_mul_f32_e32 v158, s2, v16
	v_mul_f32_e32 v159, s2, v17
	v_mul_f32_e32 v160, s2, v10
	v_mul_f32_e32 v161, s2, v11
	v_mul_f32_e32 v162, s2, v12
	v_mul_f32_e32 v163, s2, v13
	v_mul_f32_e32 v156, v14, v156
	v_mul_f32_e32 v157, v15, v157
	v_mul_f32_e32 v158, v16, v158
	v_mul_f32_e32 v159, v17, v159
	v_mul_f32_e32 v160, v10, v160
	v_mul_f32_e32 v161, v11, v161
	v_mul_f32_e32 v162, v12, v162
	v_mul_f32_e32 v163, v13, v163
	v_fma_f32 v156, v14, v156, v14
	v_fma_f32 v157, v15, v157, v15
	v_fma_f32 v158, v16, v158, v16
	v_fma_f32 v159, v17, v159, v17
	v_fma_f32 v160, v10, v160, v10
	v_fma_f32 v161, v11, v161, v11
	v_fma_f32 v162, v12, v162, v12
	v_fma_f32 v163, v13, v163, v13
	v_mul_f32_e32 v156, s3, v156
	v_mul_f32_e32 v157, s3, v157
	v_mul_f32_e32 v158, s3, v158
	v_mul_f32_e32 v159, s3, v159
	v_mul_f32_e32 v160, s3, v160
	v_mul_f32_e32 v161, s3, v161
	v_mul_f32_e32 v162, s3, v162
	v_mul_f32_e32 v163, s3, v163
	v_mul_f32_e32 v156, -2.0, v156
	v_mul_f32_e32 v157, -2.0, v157
	v_mul_f32_e32 v158, -2.0, v158
	v_mul_f32_e32 v159, -2.0, v159
	v_mul_f32_e32 v160, -2.0, v160
	v_mul_f32_e32 v161, -2.0, v161
	v_mul_f32_e32 v162, -2.0, v162
	v_mul_f32_e32 v163, -2.0, v163
	v_mul_f32_e32 v156, s28, v156
	v_mul_f32_e32 v157, s28, v157
	v_mul_f32_e32 v158, s28, v158
	v_mul_f32_e32 v159, s28, v159
	v_mul_f32_e32 v160, s28, v160
	v_mul_f32_e32 v161, s28, v161
	v_mul_f32_e32 v162, s28, v162
	v_mul_f32_e32 v163, s28, v163
	v_exp_f32_e32 v156, v156
	v_exp_f32_e32 v157, v157
	v_exp_f32_e32 v158, v158
	v_exp_f32_e32 v159, v159
	v_exp_f32_e32 v160, v160
	v_exp_f32_e32 v161, v161
	v_exp_f32_e32 v162, v162
	v_exp_f32_e32 v163, v163
	v_add_f32_e32 v156, 1.0, v156
	v_add_f32_e32 v157, 1.0, v157
	v_add_f32_e32 v158, 1.0, v158
	v_add_f32_e32 v159, 1.0, v159
	v_add_f32_e32 v160, 1.0, v160
	v_add_f32_e32 v161, 1.0, v161
	v_add_f32_e32 v162, 1.0, v162
	v_add_f32_e32 v163, 1.0, v163
	v_rcp_f32_e32 v156, v156
	v_rcp_f32_e32 v157, v157
	v_rcp_f32_e32 v158, v158
	v_rcp_f32_e32 v159, v159
	v_rcp_f32_e32 v160, v160
	v_rcp_f32_e32 v161, v161
	v_rcp_f32_e32 v162, v162
	v_rcp_f32_e32 v163, v163
	v_mul_f32_e32 v14, v14, v156
	v_mul_f32_e32 v15, v15, v157
	v_mul_f32_e32 v16, v16, v158
	v_mul_f32_e32 v17, v17, v159
	v_mul_f32_e32 v10, v10, v160
	v_mul_f32_e32 v11, v11, v161
	v_mul_f32_e32 v12, v12, v162
	v_mul_f32_e32 v13, v13, v163
	v_add_u32_e32 v153, 0x26400, v153
	v_cvt_pk_bf16_f32 v164, v14, v15
	v_cvt_pk_bf16_f32 v165, v16, v17
	v_cvt_pk_bf16_f32 v166, v10, v11
	v_cvt_pk_bf16_f32 v167, v12, v13
	s_mov_b64 exec, s[24:25]
	global_store_dwordx4 v153, v[164:167], s[68:69]
	s_mov_b64 exec, -1
	v_mul_f32_e32 v6, v6, v141
	v_mul_f32_e32 v7, v7, v141
	v_mul_f32_e32 v8, v8, v141
	v_mul_f32_e32 v9, v9, v141
	v_mul_f32_e32 v2, v2, v141
	v_mul_f32_e32 v3, v3, v141
	v_mul_f32_e32 v4, v4, v141
	v_mul_f32_e32 v5, v5, v141
	v_mul_f32_e32 v156, s2, v6
	v_mul_f32_e32 v157, s2, v7
	v_mul_f32_e32 v158, s2, v8
	v_mul_f32_e32 v159, s2, v9
	v_mul_f32_e32 v160, s2, v2
	v_mul_f32_e32 v161, s2, v3
	v_mul_f32_e32 v162, s2, v4
	v_mul_f32_e32 v163, s2, v5
	v_mul_f32_e32 v156, v6, v156
	v_mul_f32_e32 v157, v7, v157
	v_mul_f32_e32 v158, v8, v158
	v_mul_f32_e32 v159, v9, v159
	v_mul_f32_e32 v160, v2, v160
	v_mul_f32_e32 v161, v3, v161
	v_mul_f32_e32 v162, v4, v162
	v_mul_f32_e32 v163, v5, v163
	v_fma_f32 v156, v6, v156, v6
	v_fma_f32 v157, v7, v157, v7
	v_fma_f32 v158, v8, v158, v8
	v_fma_f32 v159, v9, v159, v9
	v_fma_f32 v160, v2, v160, v2
; __device__ __forceinline__ u32x4 pack8(const float* f) { u32x4 o; o.x = pk2(f[0], f[1]); o.y = pk2(f[2], f[3]); o.z = pk2(f[4], f[5]); o.w = pk2(f[6], f[7]); return o; }
; __device__ __forceinline__ float sigmoidf_(float x) { return rcpf(1.0f + __expf(-x)); }
; __device__ __forceinline__ float gelu_tanh(float v) { const float u = 0.7978845608f * (v + 0.044715f * v * v * v); return v * rcpf(1.0f + __expf(-2.0f * u)); }
;     __device__ __forceinline__ void operator()(const f32x4 (&acc)[2][2][4][2], const Unit& u, int wr, int wc, int fr, int fq) const {
;     ...
;             for (int m = 0; m < 4; ++m) { const size_t row = (size_t)(row0 + ai * HALF + m * 16); const float rs = rsv[ai][m];
; #pragma unroll
;                 for (int bj = 0; bj < 2; ++bj) { float o[8];
;                     const int c0 = u.pn * BM + bj * HALF + wc * 32 + 8 * fq;
; #pragma unroll
;                     for (int n = 0; n < 2; ++n)
; #pragma unroll
;                         for (int j = 0; j < 4; ++j) { const float v = acc[ai][bj][m][n][j] * rs; o[n * 4 + j] = mode == 0 ? gelu_tanh(v) : (mode == 1 ? v : sigmoidf_(v)); }
;                     if (mode == 2) { unsigned w0 = 0u, w1 = 0u;
; #pragma unroll
;                         for (int j = 0; j < 4; ++j) { w0 = __builtin_amdgcn_cvt_pk_u8_f32(fmaxf(o[j] * 255.f, 1.f), j, w0); w1 = __builtin_amdgcn_cvt_pk_u8_f32(fmaxf(o[4 + j] * 255.f, 1.f), j, w1); }
;                         u32x2 wv; wv.x = w0; wv.y = w1; *(u32x2*)(gates + row * 4096 + (c0 - 5120)) = wv; }
;                     else if (c0 < PLD) *(u32x4*)(proj + row * PLD + c0) = pack8(o); } }
	v_fma_f32 v161, v3, v161, v3
	v_fma_f32 v162, v4, v162, v4
	v_fma_f32 v163, v5, v163, v5
	v_mul_f32_e32 v156, s3, v156
	v_mul_f32_e32 v157, s3, v157
	v_mul_f32_e32 v158, s3, v158
	v_mul_f32_e32 v159, s3, v159
	v_mul_f32_e32 v160, s3, v160
	v_mul_f32_e32 v161, s3, v161
	v_mul_f32_e32 v162, s3, v162
	v_mul_f32_e32 v163, s3, v163
	v_mul_f32_e32 v156, -2.0, v156
	v_mul_f32_e32 v157, -2.0, v157
	v_mul_f32_e32 v158, -2.0, v158
	v_mul_f32_e32 v159, -2.0, v159
	v_mul_f32_e32 v160, -2.0, v160
	v_mul_f32_e32 v161, -2.0, v161
	v_mul_f32_e32 v162, -2.0, v162
	v_mul_f32_e32 v163, -2.0, v163
	v_mul_f32_e32 v156, s28, v156
	v_mul_f32_e32 v157, s28, v157
	v_mul_f32_e32 v158, s28, v158
	v_mul_f32_e32 v159, s28, v159
	v_mul_f32_e32 v160, s28, v160
	v_mul_f32_e32 v161, s28, v161
	v_mul_f32_e32 v162, s28, v162
	v_mul_f32_e32 v163, s28, v163
	v_exp_f32_e32 v156, v156
	v_exp_f32_e32 v157, v157
	v_exp_f32_e32 v158, v158
	v_exp_f32_e32 v159, v159
	v_exp_f32_e32 v160, v160
	v_exp_f32_e32 v161, v161
	v_exp_f32_e32 v162, v162
	v_exp_f32_e32 v163, v163
	v_add_f32_e32 v156, 1.0, v156
	v_add_f32_e32 v157, 1.0, v157
	v_add_f32_e32 v158, 1.0, v158
	v_add_f32_e32 v159, 1.0, v159
	v_add_f32_e32 v160, 1.0, v160
	v_add_f32_e32 v161, 1.0, v161
	v_add_f32_e32 v162, 1.0, v162
	v_add_f32_e32 v163, 1.0, v163
	v_rcp_f32_e32 v156, v156
	v_rcp_f32_e32 v157, v157
	v_rcp_f32_e32 v158, v158
	v_rcp_f32_e32 v159, v159
	v_rcp_f32_e32 v160, v160
	v_rcp_f32_e32 v161, v161
	v_rcp_f32_e32 v162, v162
	v_rcp_f32_e32 v163, v163
	v_mul_f32_e32 v6, v6, v156
	v_mul_f32_e32 v7, v7, v157
	v_mul_f32_e32 v8, v8, v158
	v_mul_f32_e32 v9, v9, v159
	v_mul_f32_e32 v2, v2, v160
	v_mul_f32_e32 v3, v3, v161
	v_mul_f32_e32 v4, v4, v162
	v_mul_f32_e32 v5, v5, v163
	v_cvt_pk_bf16_f32 v168, v6, v7
	v_cvt_pk_bf16_f32 v169, v8, v9
	v_cvt_pk_bf16_f32 v170, v2, v3
	v_cvt_pk_bf16_f32 v171, v4, v5
	s_mov_b64 exec, s[100:101]
	global_store_dwordx4 v153, v[168:171], s[68:69] offset:256
	s_mov_b64 exec, -1
	s_branch .Lmy_ip_done
.Lmy_ip_m1:
	v_mul_f32_e32 v126, v126, v146
	v_mul_f32_e32 v127, v127, v146
	v_mul_f32_e32 v128, v128, v146
	v_mul_f32_e32 v129, v129, v146
	v_mul_f32_e32 v122, v122, v146
	v_mul_f32_e32 v123, v123, v146
	v_mul_f32_e32 v124, v124, v146
	v_mul_f32_e32 v125, v125, v146
	v_cvt_pk_bf16_f32 v164, v126, v127
	v_cvt_pk_bf16_f32 v165, v128, v129
	v_cvt_pk_bf16_f32 v166, v122, v123
	v_cvt_pk_bf16_f32 v167, v124, v125
	s_mov_b64 exec, s[24:25]
	global_store_dwordx4 v153, v[164:167], s[68:69]
	s_mov_b64 exec, -1
	v_mul_f32_e32 v118, v118, v146
	v_mul_f32_e32 v119, v119, v146
	v_mul_f32_e32 v120, v120, v146
	v_mul_f32_e32 v121, v121, v146
	v_mul_f32_e32 v114, v114, v146
	v_mul_f32_e32 v115, v115, v146
	v_mul_f32_e32 v116, v116, v146
	v_mul_f32_e32 v117, v117, v146
	v_cvt_pk_bf16_f32 v168, v118, v119
	v_cvt_pk_bf16_f32 v169, v120, v121
	v_cvt_pk_bf16_f32 v170, v114, v115
	v_cvt_pk_bf16_f32 v171, v116, v117
	s_mov_b64 exec, s[100:101]
	global_store_dwordx4 v153, v[168:171], s[68:69] offset:256
	s_mov_b64 exec, -1
	v_mul_f32_e32 v110, v110, v147
	v_mul_f32_e32 v111, v111, v147
	v_mul_f32_e32 v112, v112, v147
	v_mul_f32_e32 v113, v113, v147
	v_mul_f32_e32 v106, v106, v147
	v_mul_f32_e32 v107, v107, v147
	v_mul_f32_e32 v108, v108, v147
	v_mul_f32_e32 v109, v109, v147
	v_add_u32_e32 v153, 0x26400, v153
	v_cvt_pk_bf16_f32 v164, v110, v111
	v_cvt_pk_bf16_f32 v165, v112, v113
	v_cvt_pk_bf16_f32 v166, v106, v107
	v_cvt_pk_bf16_f32 v167, v108, v109
	s_mov_b64 exec, s[24:25]
	global_store_dwordx4 v153, v[164:167], s[68:69]
	s_mov_b64 exec, -1
	v_mul_f32_e32 v102, v102, v147
	v_mul_f32_e32 v103, v103, v147
	v_mul_f32_e32 v104, v104, v147
	v_mul_f32_e32 v105, v105, v147
	v_mul_f32_e32 v98, v98, v147
	v_mul_f32_e32 v99, v99, v147
	v_mul_f32_e32 v100, v100, v147
	v_mul_f32_e32 v101, v101, v147
	v_cvt_pk_bf16_f32 v168, v102, v103
	v_cvt_pk_bf16_f32 v169, v104, v105
	v_cvt_pk_bf16_f32 v170, v98, v99
	v_cvt_pk_bf16_f32 v171, v100, v101
	s_mov_b64 exec, s[100:101]
	global_store_dwordx4 v153, v[168:171], s[68:69] offset:256
	s_mov_b64 exec, -1
	v_mul_f32_e32 v94, v94, v144
	v_mul_f32_e32 v95, v95, v144
	v_mul_f32_e32 v96, v96, v144
	v_mul_f32_e32 v97, v97, v144
	v_mul_f32_e32 v90, v90, v144
	v_mul_f32_e32 v91, v91, v144
	v_mul_f32_e32 v92, v92, v144
	v_mul_f32_e32 v93, v93, v144
	v_add_u32_e32 v153, 0x26400, v153
	v_cvt_pk_bf16_f32 v164, v94, v95
	v_cvt_pk_bf16_f32 v165, v96, v97
	v_cvt_pk_bf16_f32 v166, v90, v91
	v_cvt_pk_bf16_f32 v167, v92, v93
	s_mov_b64 exec, s[24:25]
	global_store_dwordx4 v153, v[164:167], s[68:69]
	s_mov_b64 exec, -1
	v_mul_f32_e32 v86, v86, v144
	v_mul_f32_e32 v87, v87, v144
	v_mul_f32_e32 v88, v88, v144
	v_mul_f32_e32 v89, v89, v144
	v_mul_f32_e32 v82, v82, v144
	v_mul_f32_e32 v83, v83, v144
	v_mul_f32_e32 v84, v84, v144
	v_mul_f32_e32 v85, v85, v144
	v_cvt_pk_bf16_f32 v168, v86, v87
	v_cvt_pk_bf16_f32 v169, v88, v89
	v_cvt_pk_bf16_f32 v170, v82, v83
	v_cvt_pk_bf16_f32 v171, v84, v85
	s_mov_b64 exec, s[100:101]
	global_store_dwordx4 v153, v[168:171], s[68:69] offset:256
	s_mov_b64 exec, -1
	v_mul_f32_e32 v78, v78, v145
	v_mul_f32_e32 v79, v79, v145
	v_mul_f32_e32 v80, v80, v145
	v_mul_f32_e32 v81, v81, v145
	v_mul_f32_e32 v74, v74, v145
	v_mul_f32_e32 v75, v75, v145
	v_mul_f32_e32 v76, v76, v145
	v_mul_f32_e32 v77, v77, v145
	v_add_u32_e32 v153, 0x26400, v153
	v_cvt_pk_bf16_f32 v164, v78, v79
	v_cvt_pk_bf16_f32 v165, v80, v81
	v_cvt_pk_bf16_f32 v166, v74, v75
	v_cvt_pk_bf16_f32 v167, v76, v77
	s_mov_b64 exec, s[24:25]
	global_store_dwordx4 v153, v[164:167], s[68:69]
	s_mov_b64 exec, -1
	v_mul_f32_e32 v70, v70, v145
	v_mul_f32_e32 v71, v71, v145
	v_mul_f32_e32 v72, v72, v145
	v_mul_f32_e32 v73, v73, v145
; __device__ __forceinline__ u32x4 pack8(const float* f) { u32x4 o; o.x = pk2(f[0], f[1]); o.y = pk2(f[2], f[3]); o.z = pk2(f[4], f[5]); o.w = pk2(f[6], f[7]); return o; }
; __device__ __forceinline__ float sigmoidf_(float x) { return rcpf(1.0f + __expf(-x)); }
; __device__ __forceinline__ float gelu_tanh(float v) { const float u = 0.7978845608f * (v + 0.044715f * v * v * v); return v * rcpf(1.0f + __expf(-2.0f * u)); }
;     __device__ __forceinline__ void operator()(const f32x4 (&acc)[2][2][4][2], const Unit& u, int wr, int wc, int fr, int fq) const {
;     ...
;             for (int m = 0; m < 4; ++m) { const size_t row = (size_t)(row0 + ai * HALF + m * 16); const float rs = rsv[ai][m];
; #pragma unroll
;                 for (int bj = 0; bj < 2; ++bj) { float o[8];
;                     const int c0 = u.pn * BM + bj * HALF + wc * 32 + 8 * fq;
; #pragma unroll
;                     for (int n = 0; n < 2; ++n)
; #pragma unroll
;                         for (int j = 0; j < 4; ++j) { const float v = acc[ai][bj][m][n][j] * rs; o[n * 4 + j] = mode == 0 ? gelu_tanh(v) : (mode == 1 ? v : sigmoidf_(v)); }
;                     if (mode == 2) { unsigned w0 = 0u, w1 = 0u;
; #pragma unroll
;                         for (int j = 0; j < 4; ++j) { w0 = __builtin_amdgcn_cvt_pk_u8_f32(fmaxf(o[j] * 255.f, 1.f), j, w0); w1 = __builtin_amdgcn_cvt_pk_u8_f32(fmaxf(o[4 + j] * 255.f, 1.f), j, w1); }
;                         u32x2 wv; wv.x = w0; wv.y = w1; *(u32x2*)(gates + row * 4096 + (c0 - 5120)) = wv; }
;                     else if (c0 < PLD) *(u32x4*)(proj + row * PLD + c0) = pack8(o); } }
	v_mul_f32_e32 v66, v66, v145
	v_mul_f32_e32 v67, v67, v145
	v_mul_f32_e32 v68, v68, v145
	v_mul_f32_e32 v69, v69, v145
	v_cvt_pk_bf16_f32 v168, v70, v71
	v_cvt_pk_bf16_f32 v169, v72, v73
	v_cvt_pk_bf16_f32 v170, v66, v67
	v_cvt_pk_bf16_f32 v171, v68, v69
	s_mov_b64 exec, s[100:101]
	global_store_dwordx4 v153, v[168:171], s[68:69] offset:256
	s_mov_b64 exec, -1
	v_mul_f32_e32 v62, v62, v142
	v_mul_f32_e32 v63, v63, v142
	v_mul_f32_e32 v64, v64, v142
	v_mul_f32_e32 v65, v65, v142
	v_mul_f32_e32 v58, v58, v142
	v_mul_f32_e32 v59, v59, v142
	v_mul_f32_e32 v60, v60, v142
	v_mul_f32_e32 v61, v61, v142
	v_add_u32_e32 v153, 0xbf400, v153
	v_cvt_pk_bf16_f32 v164, v62, v63
	v_cvt_pk_bf16_f32 v165, v64, v65
	v_cvt_pk_bf16_f32 v166, v58, v59
	v_cvt_pk_bf16_f32 v167, v60, v61
	s_mov_b64 exec, s[24:25]
	global_store_dwordx4 v153, v[164:167], s[68:69]
	s_mov_b64 exec, -1
	v_mul_f32_e32 v54, v54, v142
	v_mul_f32_e32 v55, v55, v142
	v_mul_f32_e32 v56, v56, v142
	v_mul_f32_e32 v57, v57, v142
	v_mul_f32_e32 v50, v50, v142
	v_mul_f32_e32 v51, v51, v142
	v_mul_f32_e32 v52, v52, v142
	v_mul_f32_e32 v53, v53, v142
	v_cvt_pk_bf16_f32 v168, v54, v55
	v_cvt_pk_bf16_f32 v169, v56, v57
	v_cvt_pk_bf16_f32 v170, v50, v51
	v_cvt_pk_bf16_f32 v171, v52, v53
	s_mov_b64 exec, s[100:101]
	global_store_dwordx4 v153, v[168:171], s[68:69] offset:256
	s_mov_b64 exec, -1
	v_mul_f32_e32 v46, v46, v143
	v_mul_f32_e32 v47, v47, v143
	v_mul_f32_e32 v48, v48, v143
	v_mul_f32_e32 v49, v49, v143
	v_mul_f32_e32 v42, v42, v143
	v_mul_f32_e32 v43, v43, v143
	v_mul_f32_e32 v44, v44, v143
	v_mul_f32_e32 v45, v45, v143
	v_add_u32_e32 v153, 0x26400, v153
	v_cvt_pk_bf16_f32 v164, v46, v47
	v_cvt_pk_bf16_f32 v165, v48, v49
	v_cvt_pk_bf16_f32 v166, v42, v43
	v_cvt_pk_bf16_f32 v167, v44, v45
	s_mov_b64 exec, s[24:25]
	global_store_dwordx4 v153, v[164:167], s[68:69]
	s_mov_b64 exec, -1
	v_mul_f32_e32 v38, v38, v143
	v_mul_f32_e32 v39, v39, v143
	v_mul_f32_e32 v40, v40, v143
	v_mul_f32_e32 v41, v41, v143
	v_mul_f32_e32 v34, v34, v143
	v_mul_f32_e32 v35, v35, v143
	v_mul_f32_e32 v36, v36, v143
	v_mul_f32_e32 v37, v37, v143
	v_cvt_pk_bf16_f32 v168, v38, v39
	v_cvt_pk_bf16_f32 v169, v40, v41
	v_cvt_pk_bf16_f32 v170, v34, v35
	v_cvt_pk_bf16_f32 v171, v36, v37
	s_mov_b64 exec, s[100:101]
	global_store_dwordx4 v153, v[168:171], s[68:69] offset:256
	s_mov_b64 exec, -1
	v_mul_f32_e32 v30, v30, v140
	v_mul_f32_e32 v31, v31, v140
	v_mul_f32_e32 v32, v32, v140
	v_mul_f32_e32 v33, v33, v140
	v_mul_f32_e32 v26, v26, v140
	v_mul_f32_e32 v27, v27, v140
	v_mul_f32_e32 v28, v28, v140
	v_mul_f32_e32 v29, v29, v140
	v_add_u32_e32 v153, 0x26400, v153
	v_cvt_pk_bf16_f32 v164, v30, v31
	v_cvt_pk_bf16_f32 v165, v32, v33
	v_cvt_pk_bf16_f32 v166, v26, v27
	v_cvt_pk_bf16_f32 v167, v28, v29
	s_mov_b64 exec, s[24:25]
	global_store_dwordx4 v153, v[164:167], s[68:69]
	s_mov_b64 exec, -1
	v_mul_f32_e32 v22, v22, v140
	v_mul_f32_e32 v23, v23, v140
	v_mul_f32_e32 v24, v24, v140
	v_mul_f32_e32 v25, v25, v140
	v_mul_f32_e32 v18, v18, v140
	v_mul_f32_e32 v19, v19, v140
	v_mul_f32_e32 v20, v20, v140
	v_mul_f32_e32 v21, v21, v140
	v_cvt_pk_bf16_f32 v168, v22, v23
	v_cvt_pk_bf16_f32 v169, v24, v25
	v_cvt_pk_bf16_f32 v170, v18, v19
	v_cvt_pk_bf16_f32 v171, v20, v21
	s_mov_b64 exec, s[100:101]
	global_store_dwordx4 v153, v[168:171], s[68:69] offset:256
	s_mov_b64 exec, -1
	v_mul_f32_e32 v14, v14, v141
	v_mul_f32_e32 v15, v15, v141
	v_mul_f32_e32 v16, v16, v141
	v_mul_f32_e32 v17, v17, v141
	v_mul_f32_e32 v10, v10, v141
	v_mul_f32_e32 v11, v11, v141
	v_mul_f32_e32 v12, v12, v141
	v_mul_f32_e32 v13, v13, v141
	v_add_u32_e32 v153, 0x26400, v153
	v_cvt_pk_bf16_f32 v164, v14, v15
	v_cvt_pk_bf16_f32 v165, v16, v17
	v_cvt_pk_bf16_f32 v166, v10, v11
	v_cvt_pk_bf16_f32 v167, v12, v13
	s_mov_b64 exec, s[24:25]
	global_store_dwordx4 v153, v[164:167], s[68:69]
	s_mov_b64 exec, -1
	v_mul_f32_e32 v6, v6, v141
	v_mul_f32_e32 v7, v7, v141
	v_mul_f32_e32 v8, v8, v141
	v_mul_f32_e32 v9, v9, v141
	v_mul_f32_e32 v2, v2, v141
	v_mul_f32_e32 v3, v3, v141
	v_mul_f32_e32 v4, v4, v141
	v_mul_f32_e32 v5, v5, v141
	v_cvt_pk_bf16_f32 v168, v6, v7
	v_cvt_pk_bf16_f32 v169, v8, v9
	v_cvt_pk_bf16_f32 v170, v2, v3
	v_cvt_pk_bf16_f32 v171, v4, v5
	s_mov_b64 exec, s[100:101]
	global_store_dwordx4 v153, v[168:171], s[68:69] offset:256
	s_mov_b64 exec, -1
	s_branch .Lmy_ip_done
; __device__ __forceinline__ float sigmoidf_(float x) { return rcpf(1.0f + __expf(-x)); }
; __device__ __forceinline__ float gelu_tanh(float v) { const float u = 0.7978845608f * (v + 0.044715f * v * v * v); return v * rcpf(1.0f + __expf(-2.0f * u)); }
;     __device__ __forceinline__ void operator()(const f32x4 (&acc)[2][2][4][2], const Unit& u, int wr, int wc, int fr, int fq) const {
;     ...
;             for (int m = 0; m < 4; ++m) { const size_t row = (size_t)(row0 + ai * HALF + m * 16); const float rs = rsv[ai][m];
; #pragma unroll
;                 for (int bj = 0; bj < 2; ++bj) { float o[8];
;                     const int c0 = u.pn * BM + bj * HALF + wc * 32 + 8 * fq;
; #pragma unroll
;                     for (int n = 0; n < 2; ++n)
; #pragma unroll
;                         for (int j = 0; j < 4; ++j) { const float v = acc[ai][bj][m][n][j] * rs; o[n * 4 + j] = mode == 0 ? gelu_tanh(v) : (mode == 1 ? v : sigmoidf_(v)); }
;                     if (mode == 2) { unsigned w0 = 0u, w1 = 0u;
; #pragma unroll
;                         for (int j = 0; j < 4; ++j) { w0 = __builtin_amdgcn_cvt_pk_u8_f32(fmaxf(o[j] * 255.f, 1.f), j, w0); w1 = __builtin_amdgcn_cvt_pk_u8_f32(fmaxf(o[4 + j] * 255.f, 1.f), j, w1); }
;                         u32x2 wv; wv.x = w0; wv.y = w1; *(u32x2*)(gates + row * 4096 + (c0 - 5120)) = wv; }
.Lmy_ip_m2:
	v_readlane_b32 s24, v251, 34
	v_readlane_b32 s25, v251, 35
	s_mov_b32 s2, 0xbfb8aa3b
	s_mov_b32 s3, 0x437f0000
	s_add_i32 s28, s30, -20
	s_lshl_b32 s28, s28, 8
	v_lshlrev_b32_e32 v153, 12, v153
	v_add_u32_e32 v153, v153, v151
	s_add_u32 s24, s24, s28
	s_addc_u32 s25, s25, 0
	s_waitcnt lgkmcnt(0)
	v_mul_f32_e32 v126, v126, v146
	v_mul_f32_e32 v127, v127, v146
	v_mul_f32_e32 v128, v128, v146
	v_mul_f32_e32 v129, v129, v146
	v_mul_f32_e32 v122, v122, v146
	v_mul_f32_e32 v123, v123, v146
	v_mul_f32_e32 v124, v124, v146
	v_mul_f32_e32 v125, v125, v146
	v_mul_f32_e32 v126, s2, v126
	v_mul_f32_e32 v127, s2, v127
	v_mul_f32_e32 v128, s2, v128
	v_mul_f32_e32 v129, s2, v129
	v_mul_f32_e32 v122, s2, v122
	v_mul_f32_e32 v123, s2, v123
	v_mul_f32_e32 v124, s2, v124
	v_mul_f32_e32 v125, s2, v125
	v_exp_f32_e32 v126, v126
	v_exp_f32_e32 v127, v127
	v_exp_f32_e32 v128, v128
	v_exp_f32_e32 v129, v129
	v_exp_f32_e32 v122, v122
	v_exp_f32_e32 v123, v123
	v_exp_f32_e32 v124, v124
	v_exp_f32_e32 v125, v125
	v_add_f32_e32 v126, 1.0, v126
	v_add_f32_e32 v127, 1.0, v127
	v_add_f32_e32 v128, 1.0, v128
	v_add_f32_e32 v129, 1.0, v129
	v_add_f32_e32 v122, 1.0, v122
	v_add_f32_e32 v123, 1.0, v123
	v_add_f32_e32 v124, 1.0, v124
	v_add_f32_e32 v125, 1.0, v125
	v_rcp_f32_e32 v126, v126
	v_rcp_f32_e32 v127, v127
	v_rcp_f32_e32 v128, v128
	v_rcp_f32_e32 v129, v129
	v_rcp_f32_e32 v122, v122
	v_rcp_f32_e32 v123, v123
	v_rcp_f32_e32 v124, v124
	v_rcp_f32_e32 v125, v125
	v_mul_f32_e32 v126, s3, v126
	v_mul_f32_e32 v127, s3, v127
	v_mul_f32_e32 v128, s3, v128
	v_mul_f32_e32 v129, s3, v129
	v_mul_f32_e32 v122, s3, v122
	v_mul_f32_e32 v123, s3, v123
	v_mul_f32_e32 v124, s3, v124
	v_mul_f32_e32 v125, s3, v125
	v_max_f32_e32 v126, 1.0, v126
	v_max_f32_e32 v127, 1.0, v127
	v_max_f32_e32 v128, 1.0, v128
	v_max_f32_e32 v129, 1.0, v129
	v_max_f32_e32 v122, 1.0, v122
	v_max_f32_e32 v123, 1.0, v123
	v_max_f32_e32 v124, 1.0, v124
	v_max_f32_e32 v125, 1.0, v125
	v_cvt_pk_u8_f32 v154, v126, 0, 0
	v_cvt_pk_u8_f32 v155, v122, 0, 0
	v_cvt_pk_u8_f32 v154, v127, 1, v154
	v_cvt_pk_u8_f32 v155, v123, 1, v155
	v_cvt_pk_u8_f32 v154, v128, 2, v154
	v_cvt_pk_u8_f32 v155, v124, 2, v155
	v_cvt_pk_u8_f32 v154, v129, 3, v154
	v_cvt_pk_u8_f32 v155, v125, 3, v155
	global_store_dwordx2 v153, v[154:155], s[24:25]
	v_mul_f32_e32 v118, v118, v146
	v_mul_f32_e32 v119, v119, v146
	v_mul_f32_e32 v120, v120, v146
	v_mul_f32_e32 v121, v121, v146
	v_mul_f32_e32 v114, v114, v146
	v_mul_f32_e32 v115, v115, v146
	v_mul_f32_e32 v116, v116, v146
	v_mul_f32_e32 v117, v117, v146
	v_mul_f32_e32 v118, s2, v118
	v_mul_f32_e32 v119, s2, v119
	v_mul_f32_e32 v120, s2, v120
	v_mul_f32_e32 v121, s2, v121
	v_mul_f32_e32 v114, s2, v114
	v_mul_f32_e32 v115, s2, v115
	v_mul_f32_e32 v116, s2, v116
	v_mul_f32_e32 v117, s2, v117
	v_exp_f32_e32 v118, v118
	v_exp_f32_e32 v119, v119
	v_exp_f32_e32 v120, v120
	v_exp_f32_e32 v121, v121
	v_exp_f32_e32 v114, v114
	v_exp_f32_e32 v115, v115
	v_exp_f32_e32 v116, v116
	v_exp_f32_e32 v117, v117
	v_add_f32_e32 v118, 1.0, v118
	v_add_f32_e32 v119, 1.0, v119
	v_add_f32_e32 v120, 1.0, v120
	v_add_f32_e32 v121, 1.0, v121
	v_add_f32_e32 v114, 1.0, v114
	v_add_f32_e32 v115, 1.0, v115
	v_add_f32_e32 v116, 1.0, v116
	v_add_f32_e32 v117, 1.0, v117
	v_rcp_f32_e32 v118, v118
	v_rcp_f32_e32 v119, v119
	v_rcp_f32_e32 v120, v120
	v_rcp_f32_e32 v121, v121
	v_rcp_f32_e32 v114, v114
	v_rcp_f32_e32 v115, v115
	v_rcp_f32_e32 v116, v116
	v_rcp_f32_e32 v117, v117
	v_mul_f32_e32 v118, s3, v118
	v_mul_f32_e32 v119, s3, v119
	v_mul_f32_e32 v120, s3, v120
	v_mul_f32_e32 v121, s3, v121
	v_mul_f32_e32 v114, s3, v114
	v_mul_f32_e32 v115, s3, v115
	v_mul_f32_e32 v116, s3, v116
	v_mul_f32_e32 v117, s3, v117
	v_max_f32_e32 v118, 1.0, v118
	v_max_f32_e32 v119, 1.0, v119
	v_max_f32_e32 v120, 1.0, v120
	v_max_f32_e32 v121, 1.0, v121
	v_max_f32_e32 v114, 1.0, v114
	v_max_f32_e32 v115, 1.0, v115
	v_max_f32_e32 v116, 1.0, v116
	v_max_f32_e32 v117, 1.0, v117
	v_cvt_pk_u8_f32 v156, v118, 0, 0
	v_cvt_pk_u8_f32 v157, v114, 0, 0
	v_cvt_pk_u8_f32 v156, v119, 1, v156
	v_cvt_pk_u8_f32 v157, v115, 1, v157
	v_cvt_pk_u8_f32 v156, v120, 2, v156
	v_cvt_pk_u8_f32 v157, v116, 2, v157
	v_cvt_pk_u8_f32 v156, v121, 3, v156
	v_cvt_pk_u8_f32 v157, v117, 3, v157
	global_store_dwordx2 v153, v[156:157], s[24:25] offset:128
	v_mul_f32_e32 v110, v110, v147
	v_mul_f32_e32 v111, v111, v147
	v_mul_f32_e32 v112, v112, v147
	v_mul_f32_e32 v113, v113, v147
	v_mul_f32_e32 v106, v106, v147
	v_mul_f32_e32 v107, v107, v147
	v_mul_f32_e32 v108, v108, v147
	v_mul_f32_e32 v109, v109, v147
	v_mul_f32_e32 v110, s2, v110
	v_mul_f32_e32 v111, s2, v111
	v_mul_f32_e32 v112, s2, v112
	v_mul_f32_e32 v113, s2, v113
	v_mul_f32_e32 v106, s2, v106
	v_mul_f32_e32 v107, s2, v107
	v_mul_f32_e32 v108, s2, v108
	v_mul_f32_e32 v109, s2, v109
	v_exp_f32_e32 v110, v110
	v_exp_f32_e32 v111, v111
	v_exp_f32_e32 v112, v112
	v_exp_f32_e32 v113, v113
	v_exp_f32_e32 v106, v106
	v_exp_f32_e32 v107, v107
	v_exp_f32_e32 v108, v108
	v_exp_f32_e32 v109, v109
	v_add_f32_e32 v110, 1.0, v110
	v_add_f32_e32 v111, 1.0, v111
	v_add_f32_e32 v112, 1.0, v112
	v_add_f32_e32 v113, 1.0, v113
	v_add_f32_e32 v106, 1.0, v106
	v_add_f32_e32 v107, 1.0, v107
	v_add_f32_e32 v108, 1.0, v108
	v_add_f32_e32 v109, 1.0, v109
	v_rcp_f32_e32 v110, v110
	v_rcp_f32_e32 v111, v111
	v_rcp_f32_e32 v112, v112
	v_rcp_f32_e32 v113, v113
	v_rcp_f32_e32 v106, v106
	v_rcp_f32_e32 v107, v107
	v_rcp_f32_e32 v108, v108
	v_rcp_f32_e32 v109, v109
	v_mul_f32_e32 v110, s3, v110
	v_mul_f32_e32 v111, s3, v111
	v_mul_f32_e32 v112, s3, v112
	v_mul_f32_e32 v113, s3, v113
	v_mul_f32_e32 v106, s3, v106
	v_mul_f32_e32 v107, s3, v107
; __device__ __forceinline__ float sigmoidf_(float x) { return rcpf(1.0f + __expf(-x)); }
; __device__ __forceinline__ float gelu_tanh(float v) { const float u = 0.7978845608f * (v + 0.044715f * v * v * v); return v * rcpf(1.0f + __expf(-2.0f * u)); }
;     __device__ __forceinline__ void operator()(const f32x4 (&acc)[2][2][4][2], const Unit& u, int wr, int wc, int fr, int fq) const {
;     ...
;             for (int m = 0; m < 4; ++m) { const size_t row = (size_t)(row0 + ai * HALF + m * 16); const float rs = rsv[ai][m];
; #pragma unroll
;                 for (int bj = 0; bj < 2; ++bj) { float o[8];
;                     const int c0 = u.pn * BM + bj * HALF + wc * 32 + 8 * fq;
; #pragma unroll
;                     for (int n = 0; n < 2; ++n)
; #pragma unroll
;                         for (int j = 0; j < 4; ++j) { const float v = acc[ai][bj][m][n][j] * rs; o[n * 4 + j] = mode == 0 ? gelu_tanh(v) : (mode == 1 ? v : sigmoidf_(v)); }
;                     if (mode == 2) { unsigned w0 = 0u, w1 = 0u;
; #pragma unroll
;                         for (int j = 0; j < 4; ++j) { w0 = __builtin_amdgcn_cvt_pk_u8_f32(fmaxf(o[j] * 255.f, 1.f), j, w0); w1 = __builtin_amdgcn_cvt_pk_u8_f32(fmaxf(o[4 + j] * 255.f, 1.f), j, w1); }
;                         u32x2 wv; wv.x = w0; wv.y = w1; *(u32x2*)(gates + row * 4096 + (c0 - 5120)) = wv; }
	v_mul_f32_e32 v108, s3, v108
	v_mul_f32_e32 v109, s3, v109
	v_max_f32_e32 v110, 1.0, v110
	v_max_f32_e32 v111, 1.0, v111
	v_max_f32_e32 v112, 1.0, v112
	v_max_f32_e32 v113, 1.0, v113
	v_max_f32_e32 v106, 1.0, v106
	v_max_f32_e32 v107, 1.0, v107
	v_max_f32_e32 v108, 1.0, v108
	v_max_f32_e32 v109, 1.0, v109
	v_cvt_pk_u8_f32 v154, v110, 0, 0
	v_cvt_pk_u8_f32 v155, v106, 0, 0
	v_cvt_pk_u8_f32 v154, v111, 1, v154
	v_cvt_pk_u8_f32 v155, v107, 1, v155
	v_cvt_pk_u8_f32 v154, v112, 2, v154
	v_cvt_pk_u8_f32 v155, v108, 2, v155
	v_cvt_pk_u8_f32 v154, v113, 3, v154
	v_cvt_pk_u8_f32 v155, v109, 3, v155
	v_add_u32_e32 v153, 0x10000, v153
	global_store_dwordx2 v153, v[154:155], s[24:25]
	v_mul_f32_e32 v102, v102, v147
	v_mul_f32_e32 v103, v103, v147
	v_mul_f32_e32 v104, v104, v147
	v_mul_f32_e32 v105, v105, v147
	v_mul_f32_e32 v98, v98, v147
	v_mul_f32_e32 v99, v99, v147
	v_mul_f32_e32 v100, v100, v147
	v_mul_f32_e32 v101, v101, v147
	v_mul_f32_e32 v102, s2, v102
	v_mul_f32_e32 v103, s2, v103
	v_mul_f32_e32 v104, s2, v104
	v_mul_f32_e32 v105, s2, v105
	v_mul_f32_e32 v98, s2, v98
	v_mul_f32_e32 v99, s2, v99
	v_mul_f32_e32 v100, s2, v100
	v_mul_f32_e32 v101, s2, v101
	v_exp_f32_e32 v102, v102
	v_exp_f32_e32 v103, v103
	v_exp_f32_e32 v104, v104
	v_exp_f32_e32 v105, v105
	v_exp_f32_e32 v98, v98
	v_exp_f32_e32 v99, v99
	v_exp_f32_e32 v100, v100
	v_exp_f32_e32 v101, v101
	v_add_f32_e32 v102, 1.0, v102
	v_add_f32_e32 v103, 1.0, v103
	v_add_f32_e32 v104, 1.0, v104
	v_add_f32_e32 v105, 1.0, v105
	v_add_f32_e32 v98, 1.0, v98
	v_add_f32_e32 v99, 1.0, v99
	v_add_f32_e32 v100, 1.0, v100
	v_add_f32_e32 v101, 1.0, v101
	v_rcp_f32_e32 v102, v102
	v_rcp_f32_e32 v103, v103
	v_rcp_f32_e32 v104, v104
	v_rcp_f32_e32 v105, v105
	v_rcp_f32_e32 v98, v98
	v_rcp_f32_e32 v99, v99
	v_rcp_f32_e32 v100, v100
	v_rcp_f32_e32 v101, v101
	v_mul_f32_e32 v102, s3, v102
	v_mul_f32_e32 v103, s3, v103
	v_mul_f32_e32 v104, s3, v104
	v_mul_f32_e32 v105, s3, v105
	v_mul_f32_e32 v98, s3, v98
	v_mul_f32_e32 v99, s3, v99
	v_mul_f32_e32 v100, s3, v100
	v_mul_f32_e32 v101, s3, v101
	v_max_f32_e32 v102, 1.0, v102
	v_max_f32_e32 v103, 1.0, v103
	v_max_f32_e32 v104, 1.0, v104
	v_max_f32_e32 v105, 1.0, v105
	v_max_f32_e32 v98, 1.0, v98
	v_max_f32_e32 v99, 1.0, v99
	v_max_f32_e32 v100, 1.0, v100
	v_max_f32_e32 v101, 1.0, v101
	v_cvt_pk_u8_f32 v156, v102, 0, 0
	v_cvt_pk_u8_f32 v157, v98, 0, 0
	v_cvt_pk_u8_f32 v156, v103, 1, v156
	v_cvt_pk_u8_f32 v157, v99, 1, v157
	v_cvt_pk_u8_f32 v156, v104, 2, v156
	v_cvt_pk_u8_f32 v157, v100, 2, v157
	v_cvt_pk_u8_f32 v156, v105, 3, v156
	v_cvt_pk_u8_f32 v157, v101, 3, v157
	global_store_dwordx2 v153, v[156:157], s[24:25] offset:128
	v_mul_f32_e32 v94, v94, v144
	v_mul_f32_e32 v95, v95, v144
	v_mul_f32_e32 v96, v96, v144
	v_mul_f32_e32 v97, v97, v144
	v_mul_f32_e32 v90, v90, v144
	v_mul_f32_e32 v91, v91, v144
	v_mul_f32_e32 v92, v92, v144
	v_mul_f32_e32 v93, v93, v144
	v_mul_f32_e32 v94, s2, v94
	v_mul_f32_e32 v95, s2, v95
	v_mul_f32_e32 v96, s2, v96
	v_mul_f32_e32 v97, s2, v97
	v_mul_f32_e32 v90, s2, v90
	v_mul_f32_e32 v91, s2, v91
	v_mul_f32_e32 v92, s2, v92
	v_mul_f32_e32 v93, s2, v93
	v_exp_f32_e32 v94, v94
	v_exp_f32_e32 v95, v95
	v_exp_f32_e32 v96, v96
	v_exp_f32_e32 v97, v97
	v_exp_f32_e32 v90, v90
	v_exp_f32_e32 v91, v91
	v_exp_f32_e32 v92, v92
	v_exp_f32_e32 v93, v93
	v_add_f32_e32 v94, 1.0, v94
	v_add_f32_e32 v95, 1.0, v95
	v_add_f32_e32 v96, 1.0, v96
	v_add_f32_e32 v97, 1.0, v97
	v_add_f32_e32 v90, 1.0, v90
	v_add_f32_e32 v91, 1.0, v91
	v_add_f32_e32 v92, 1.0, v92
	v_add_f32_e32 v93, 1.0, v93
	v_rcp_f32_e32 v94, v94
	v_rcp_f32_e32 v95, v95
	v_rcp_f32_e32 v96, v96
	v_rcp_f32_e32 v97, v97
	v_rcp_f32_e32 v90, v90
	v_rcp_f32_e32 v91, v91
	v_rcp_f32_e32 v92, v92
	v_rcp_f32_e32 v93, v93
	v_mul_f32_e32 v94, s3, v94
	v_mul_f32_e32 v95, s3, v95
	v_mul_f32_e32 v96, s3, v96
	v_mul_f32_e32 v97, s3, v97
	v_mul_f32_e32 v90, s3, v90
	v_mul_f32_e32 v91, s3, v91
	v_mul_f32_e32 v92, s3, v92
	v_mul_f32_e32 v93, s3, v93
	v_max_f32_e32 v94, 1.0, v94
	v_max_f32_e32 v95, 1.0, v95
	v_max_f32_e32 v96, 1.0, v96
	v_max_f32_e32 v97, 1.0, v97
	v_max_f32_e32 v90, 1.0, v90
	v_max_f32_e32 v91, 1.0, v91
	v_max_f32_e32 v92, 1.0, v92
	v_max_f32_e32 v93, 1.0, v93
	v_cvt_pk_u8_f32 v154, v94, 0, 0
	v_cvt_pk_u8_f32 v155, v90, 0, 0
	v_cvt_pk_u8_f32 v154, v95, 1, v154
	v_cvt_pk_u8_f32 v155, v91, 1, v155
	v_cvt_pk_u8_f32 v154, v96, 2, v154
	v_cvt_pk_u8_f32 v155, v92, 2, v155
	v_cvt_pk_u8_f32 v154, v97, 3, v154
	v_cvt_pk_u8_f32 v155, v93, 3, v155
	v_add_u32_e32 v153, 0x10000, v153
	global_store_dwordx2 v153, v[154:155], s[24:25]
	v_mul_f32_e32 v86, v86, v144
	v_mul_f32_e32 v87, v87, v144
	v_mul_f32_e32 v88, v88, v144
	v_mul_f32_e32 v89, v89, v144
	v_mul_f32_e32 v82, v82, v144
	v_mul_f32_e32 v83, v83, v144
	v_mul_f32_e32 v84, v84, v144
	v_mul_f32_e32 v85, v85, v144
	v_mul_f32_e32 v86, s2, v86
	v_mul_f32_e32 v87, s2, v87
	v_mul_f32_e32 v88, s2, v88
	v_mul_f32_e32 v89, s2, v89
	v_mul_f32_e32 v82, s2, v82
	v_mul_f32_e32 v83, s2, v83
	v_mul_f32_e32 v84, s2, v84
	v_mul_f32_e32 v85, s2, v85
	v_exp_f32_e32 v86, v86
	v_exp_f32_e32 v87, v87
	v_exp_f32_e32 v88, v88
	v_exp_f32_e32 v89, v89
	v_exp_f32_e32 v82, v82
	v_exp_f32_e32 v83, v83
	v_exp_f32_e32 v84, v84
	v_exp_f32_e32 v85, v85
	v_add_f32_e32 v86, 1.0, v86
	v_add_f32_e32 v87, 1.0, v87
	v_add_f32_e32 v88, 1.0, v88
	v_add_f32_e32 v89, 1.0, v89
	v_add_f32_e32 v82, 1.0, v82
	v_add_f32_e32 v83, 1.0, v83
	v_add_f32_e32 v84, 1.0, v84
	v_add_f32_e32 v85, 1.0, v85
	v_rcp_f32_e32 v86, v86
	v_rcp_f32_e32 v87, v87
	v_rcp_f32_e32 v88, v88
	v_rcp_f32_e32 v89, v89
	v_rcp_f32_e32 v82, v82
	v_rcp_f32_e32 v83, v83
	v_rcp_f32_e32 v84, v84
	v_rcp_f32_e32 v85, v85
; __device__ __forceinline__ float sigmoidf_(float x) { return rcpf(1.0f + __expf(-x)); }
; __device__ __forceinline__ float gelu_tanh(float v) { const float u = 0.7978845608f * (v + 0.044715f * v * v * v); return v * rcpf(1.0f + __expf(-2.0f * u)); }
;     __device__ __forceinline__ void operator()(const f32x4 (&acc)[2][2][4][2], const Unit& u, int wr, int wc, int fr, int fq) const {
;     ...
;             for (int m = 0; m < 4; ++m) { const size_t row = (size_t)(row0 + ai * HALF + m * 16); const float rs = rsv[ai][m];
; #pragma unroll
;                 for (int bj = 0; bj < 2; ++bj) { float o[8];
;                     const int c0 = u.pn * BM + bj * HALF + wc * 32 + 8 * fq;
; #pragma unroll
;                     for (int n = 0; n < 2; ++n)
; #pragma unroll
;                         for (int j = 0; j < 4; ++j) { const float v = acc[ai][bj][m][n][j] * rs; o[n * 4 + j] = mode == 0 ? gelu_tanh(v) : (mode == 1 ? v : sigmoidf_(v)); }
;                     if (mode == 2) { unsigned w0 = 0u, w1 = 0u;
; #pragma unroll
;                         for (int j = 0; j < 4; ++j) { w0 = __builtin_amdgcn_cvt_pk_u8_f32(fmaxf(o[j] * 255.f, 1.f), j, w0); w1 = __builtin_amdgcn_cvt_pk_u8_f32(fmaxf(o[4 + j] * 255.f, 1.f), j, w1); }
;                         u32x2 wv; wv.x = w0; wv.y = w1; *(u32x2*)(gates + row * 4096 + (c0 - 5120)) = wv; }
	v_mul_f32_e32 v86, s3, v86
	v_mul_f32_e32 v87, s3, v87
	v_mul_f32_e32 v88, s3, v88
	v_mul_f32_e32 v89, s3, v89
	v_mul_f32_e32 v82, s3, v82
	v_mul_f32_e32 v83, s3, v83
	v_mul_f32_e32 v84, s3, v84
	v_mul_f32_e32 v85, s3, v85
	v_max_f32_e32 v86, 1.0, v86
	v_max_f32_e32 v87, 1.0, v87
	v_max_f32_e32 v88, 1.0, v88
	v_max_f32_e32 v89, 1.0, v89
	v_max_f32_e32 v82, 1.0, v82
	v_max_f32_e32 v83, 1.0, v83
	v_max_f32_e32 v84, 1.0, v84
	v_max_f32_e32 v85, 1.0, v85
	v_cvt_pk_u8_f32 v156, v86, 0, 0
	v_cvt_pk_u8_f32 v157, v82, 0, 0
	v_cvt_pk_u8_f32 v156, v87, 1, v156
	v_cvt_pk_u8_f32 v157, v83, 1, v157
	v_cvt_pk_u8_f32 v156, v88, 2, v156
	v_cvt_pk_u8_f32 v157, v84, 2, v157
	v_cvt_pk_u8_f32 v156, v89, 3, v156
	v_cvt_pk_u8_f32 v157, v85, 3, v157
	global_store_dwordx2 v153, v[156:157], s[24:25] offset:128
	v_mul_f32_e32 v78, v78, v145
	v_mul_f32_e32 v79, v79, v145
	v_mul_f32_e32 v80, v80, v145
	v_mul_f32_e32 v81, v81, v145
	v_mul_f32_e32 v74, v74, v145
	v_mul_f32_e32 v75, v75, v145
	v_mul_f32_e32 v76, v76, v145
	v_mul_f32_e32 v77, v77, v145
	v_mul_f32_e32 v78, s2, v78
	v_mul_f32_e32 v79, s2, v79
	v_mul_f32_e32 v80, s2, v80
	v_mul_f32_e32 v81, s2, v81
	v_mul_f32_e32 v74, s2, v74
	v_mul_f32_e32 v75, s2, v75
	v_mul_f32_e32 v76, s2, v76
	v_mul_f32_e32 v77, s2, v77
	v_exp_f32_e32 v78, v78
	v_exp_f32_e32 v79, v79
	v_exp_f32_e32 v80, v80
	v_exp_f32_e32 v81, v81
	v_exp_f32_e32 v74, v74
	v_exp_f32_e32 v75, v75
	v_exp_f32_e32 v76, v76
	v_exp_f32_e32 v77, v77
	v_add_f32_e32 v78, 1.0, v78
	v_add_f32_e32 v79, 1.0, v79
	v_add_f32_e32 v80, 1.0, v80
	v_add_f32_e32 v81, 1.0, v81
	v_add_f32_e32 v74, 1.0, v74
	v_add_f32_e32 v75, 1.0, v75
	v_add_f32_e32 v76, 1.0, v76
	v_add_f32_e32 v77, 1.0, v77
	v_rcp_f32_e32 v78, v78
	v_rcp_f32_e32 v79, v79
	v_rcp_f32_e32 v80, v80
	v_rcp_f32_e32 v81, v81
	v_rcp_f32_e32 v74, v74
	v_rcp_f32_e32 v75, v75
	v_rcp_f32_e32 v76, v76
	v_rcp_f32_e32 v77, v77
	v_mul_f32_e32 v78, s3, v78
	v_mul_f32_e32 v79, s3, v79
	v_mul_f32_e32 v80, s3, v80
	v_mul_f32_e32 v81, s3, v81
	v_mul_f32_e32 v74, s3, v74
	v_mul_f32_e32 v75, s3, v75
	v_mul_f32_e32 v76, s3, v76
	v_mul_f32_e32 v77, s3, v77
	v_max_f32_e32 v78, 1.0, v78
	v_max_f32_e32 v79, 1.0, v79
	v_max_f32_e32 v80, 1.0, v80
	v_max_f32_e32 v81, 1.0, v81
	v_max_f32_e32 v74, 1.0, v74
	v_max_f32_e32 v75, 1.0, v75
	v_max_f32_e32 v76, 1.0, v76
	v_max_f32_e32 v77, 1.0, v77
	v_cvt_pk_u8_f32 v154, v78, 0, 0
	v_cvt_pk_u8_f32 v155, v74, 0, 0
	v_cvt_pk_u8_f32 v154, v79, 1, v154
	v_cvt_pk_u8_f32 v155, v75, 1, v155
	v_cvt_pk_u8_f32 v154, v80, 2, v154
	v_cvt_pk_u8_f32 v155, v76, 2, v155
	v_cvt_pk_u8_f32 v154, v81, 3, v154
	v_cvt_pk_u8_f32 v155, v77, 3, v155
	v_add_u32_e32 v153, 0x10000, v153
	global_store_dwordx2 v153, v[154:155], s[24:25]
	v_mul_f32_e32 v70, v70, v145
	v_mul_f32_e32 v71, v71, v145
	v_mul_f32_e32 v72, v72, v145
	v_mul_f32_e32 v73, v73, v145
	v_mul_f32_e32 v66, v66, v145
	v_mul_f32_e32 v67, v67, v145
	v_mul_f32_e32 v68, v68, v145
	v_mul_f32_e32 v69, v69, v145
	v_mul_f32_e32 v70, s2, v70
	v_mul_f32_e32 v71, s2, v71
	v_mul_f32_e32 v72, s2, v72
	v_mul_f32_e32 v73, s2, v73
	v_mul_f32_e32 v66, s2, v66
	v_mul_f32_e32 v67, s2, v67
	v_mul_f32_e32 v68, s2, v68
	v_mul_f32_e32 v69, s2, v69
	v_exp_f32_e32 v70, v70
	v_exp_f32_e32 v71, v71
	v_exp_f32_e32 v72, v72
	v_exp_f32_e32 v73, v73
	v_exp_f32_e32 v66, v66
	v_exp_f32_e32 v67, v67
	v_exp_f32_e32 v68, v68
	v_exp_f32_e32 v69, v69
	v_add_f32_e32 v70, 1.0, v70
	v_add_f32_e32 v71, 1.0, v71
	v_add_f32_e32 v72, 1.0, v72
	v_add_f32_e32 v73, 1.0, v73
	v_add_f32_e32 v66, 1.0, v66
	v_add_f32_e32 v67, 1.0, v67
	v_add_f32_e32 v68, 1.0, v68
	v_add_f32_e32 v69, 1.0, v69
	v_rcp_f32_e32 v70, v70
	v_rcp_f32_e32 v71, v71
	v_rcp_f32_e32 v72, v72
	v_rcp_f32_e32 v73, v73
	v_rcp_f32_e32 v66, v66
	v_rcp_f32_e32 v67, v67
	v_rcp_f32_e32 v68, v68
	v_rcp_f32_e32 v69, v69
	v_mul_f32_e32 v70, s3, v70
	v_mul_f32_e32 v71, s3, v71
	v_mul_f32_e32 v72, s3, v72
	v_mul_f32_e32 v73, s3, v73
	v_mul_f32_e32 v66, s3, v66
	v_mul_f32_e32 v67, s3, v67
	v_mul_f32_e32 v68, s3, v68
	v_mul_f32_e32 v69, s3, v69
	v_max_f32_e32 v70, 1.0, v70
	v_max_f32_e32 v71, 1.0, v71
	v_max_f32_e32 v72, 1.0, v72
	v_max_f32_e32 v73, 1.0, v73
	v_max_f32_e32 v66, 1.0, v66
	v_max_f32_e32 v67, 1.0, v67
	v_max_f32_e32 v68, 1.0, v68
	v_max_f32_e32 v69, 1.0, v69
	v_cvt_pk_u8_f32 v156, v70, 0, 0
	v_cvt_pk_u8_f32 v157, v66, 0, 0
	v_cvt_pk_u8_f32 v156, v71, 1, v156
	v_cvt_pk_u8_f32 v157, v67, 1, v157
	v_cvt_pk_u8_f32 v156, v72, 2, v156
	v_cvt_pk_u8_f32 v157, v68, 2, v157
	v_cvt_pk_u8_f32 v156, v73, 3, v156
	v_cvt_pk_u8_f32 v157, v69, 3, v157
	global_store_dwordx2 v153, v[156:157], s[24:25] offset:128
	v_mul_f32_e32 v62, v62, v142
	v_mul_f32_e32 v63, v63, v142
	v_mul_f32_e32 v64, v64, v142
	v_mul_f32_e32 v65, v65, v142
	v_mul_f32_e32 v58, v58, v142
	v_mul_f32_e32 v59, v59, v142
	v_mul_f32_e32 v60, v60, v142
	v_mul_f32_e32 v61, v61, v142
	v_mul_f32_e32 v62, s2, v62
	v_mul_f32_e32 v63, s2, v63
	v_mul_f32_e32 v64, s2, v64
	v_mul_f32_e32 v65, s2, v65
	v_mul_f32_e32 v58, s2, v58
	v_mul_f32_e32 v59, s2, v59
	v_mul_f32_e32 v60, s2, v60
	v_mul_f32_e32 v61, s2, v61
	v_exp_f32_e32 v62, v62
	v_exp_f32_e32 v63, v63
	v_exp_f32_e32 v64, v64
	v_exp_f32_e32 v65, v65
	v_exp_f32_e32 v58, v58
	v_exp_f32_e32 v59, v59
	v_exp_f32_e32 v60, v60
	v_exp_f32_e32 v61, v61
	v_add_f32_e32 v62, 1.0, v62
	v_add_f32_e32 v63, 1.0, v63
	v_add_f32_e32 v64, 1.0, v64
	v_add_f32_e32 v65, 1.0, v65
	v_add_f32_e32 v58, 1.0, v58
	v_add_f32_e32 v59, 1.0, v59
	v_add_f32_e32 v60, 1.0, v60
	v_add_f32_e32 v61, 1.0, v61
	v_rcp_f32_e32 v62, v62
	v_rcp_f32_e32 v63, v63
	v_rcp_f32_e32 v64, v64
	v_rcp_f32_e32 v65, v65
	v_rcp_f32_e32 v58, v58
	v_rcp_f32_e32 v59, v59
	v_rcp_f32_e32 v60, v60
; __device__ __forceinline__ float sigmoidf_(float x) { return rcpf(1.0f + __expf(-x)); }
; __device__ __forceinline__ float gelu_tanh(float v) { const float u = 0.7978845608f * (v + 0.044715f * v * v * v); return v * rcpf(1.0f + __expf(-2.0f * u)); }
;     __device__ __forceinline__ void operator()(const f32x4 (&acc)[2][2][4][2], const Unit& u, int wr, int wc, int fr, int fq) const {
;     ...
;             for (int m = 0; m < 4; ++m) { const size_t row = (size_t)(row0 + ai * HALF + m * 16); const float rs = rsv[ai][m];
; #pragma unroll
;                 for (int bj = 0; bj < 2; ++bj) { float o[8];
;                     const int c0 = u.pn * BM + bj * HALF + wc * 32 + 8 * fq;
; #pragma unroll
;                     for (int n = 0; n < 2; ++n)
; #pragma unroll
;                         for (int j = 0; j < 4; ++j) { const float v = acc[ai][bj][m][n][j] * rs; o[n * 4 + j] = mode == 0 ? gelu_tanh(v) : (mode == 1 ? v : sigmoidf_(v)); }
;                     if (mode == 2) { unsigned w0 = 0u, w1 = 0u;
; #pragma unroll
;                         for (int j = 0; j < 4; ++j) { w0 = __builtin_amdgcn_cvt_pk_u8_f32(fmaxf(o[j] * 255.f, 1.f), j, w0); w1 = __builtin_amdgcn_cvt_pk_u8_f32(fmaxf(o[4 + j] * 255.f, 1.f), j, w1); }
;                         u32x2 wv; wv.x = w0; wv.y = w1; *(u32x2*)(gates + row * 4096 + (c0 - 5120)) = wv; }
	v_rcp_f32_e32 v61, v61
	v_mul_f32_e32 v62, s3, v62
	v_mul_f32_e32 v63, s3, v63
	v_mul_f32_e32 v64, s3, v64
	v_mul_f32_e32 v65, s3, v65
	v_mul_f32_e32 v58, s3, v58
	v_mul_f32_e32 v59, s3, v59
	v_mul_f32_e32 v60, s3, v60
	v_mul_f32_e32 v61, s3, v61
	v_max_f32_e32 v62, 1.0, v62
	v_max_f32_e32 v63, 1.0, v63
	v_max_f32_e32 v64, 1.0, v64
	v_max_f32_e32 v65, 1.0, v65
	v_max_f32_e32 v58, 1.0, v58
	v_max_f32_e32 v59, 1.0, v59
	v_max_f32_e32 v60, 1.0, v60
	v_max_f32_e32 v61, 1.0, v61
	v_cvt_pk_u8_f32 v154, v62, 0, 0
	v_cvt_pk_u8_f32 v155, v58, 0, 0
	v_cvt_pk_u8_f32 v154, v63, 1, v154
	v_cvt_pk_u8_f32 v155, v59, 1, v155
	v_cvt_pk_u8_f32 v154, v64, 2, v154
	v_cvt_pk_u8_f32 v155, v60, 2, v155
	v_cvt_pk_u8_f32 v154, v65, 3, v154
	v_cvt_pk_u8_f32 v155, v61, 3, v155
	v_add_u32_e32 v153, 0x50000, v153
	global_store_dwordx2 v153, v[154:155], s[24:25]
	v_mul_f32_e32 v54, v54, v142
	v_mul_f32_e32 v55, v55, v142
	v_mul_f32_e32 v56, v56, v142
	v_mul_f32_e32 v57, v57, v142
	v_mul_f32_e32 v50, v50, v142
	v_mul_f32_e32 v51, v51, v142
	v_mul_f32_e32 v52, v52, v142
	v_mul_f32_e32 v53, v53, v142
	v_mul_f32_e32 v54, s2, v54
	v_mul_f32_e32 v55, s2, v55
	v_mul_f32_e32 v56, s2, v56
	v_mul_f32_e32 v57, s2, v57
	v_mul_f32_e32 v50, s2, v50
	v_mul_f32_e32 v51, s2, v51
	v_mul_f32_e32 v52, s2, v52
	v_mul_f32_e32 v53, s2, v53
	v_exp_f32_e32 v54, v54
	v_exp_f32_e32 v55, v55
	v_exp_f32_e32 v56, v56
	v_exp_f32_e32 v57, v57
	v_exp_f32_e32 v50, v50
	v_exp_f32_e32 v51, v51
	v_exp_f32_e32 v52, v52
	v_exp_f32_e32 v53, v53
	v_add_f32_e32 v54, 1.0, v54
	v_add_f32_e32 v55, 1.0, v55
	v_add_f32_e32 v56, 1.0, v56
	v_add_f32_e32 v57, 1.0, v57
	v_add_f32_e32 v50, 1.0, v50
	v_add_f32_e32 v51, 1.0, v51
	v_add_f32_e32 v52, 1.0, v52
	v_add_f32_e32 v53, 1.0, v53
	v_rcp_f32_e32 v54, v54
	v_rcp_f32_e32 v55, v55
	v_rcp_f32_e32 v56, v56
	v_rcp_f32_e32 v57, v57
	v_rcp_f32_e32 v50, v50
	v_rcp_f32_e32 v51, v51
	v_rcp_f32_e32 v52, v52
	v_rcp_f32_e32 v53, v53
	v_mul_f32_e32 v54, s3, v54
	v_mul_f32_e32 v55, s3, v55
	v_mul_f32_e32 v56, s3, v56
	v_mul_f32_e32 v57, s3, v57
	v_mul_f32_e32 v50, s3, v50
	v_mul_f32_e32 v51, s3, v51
	v_mul_f32_e32 v52, s3, v52
	v_mul_f32_e32 v53, s3, v53
	v_max_f32_e32 v54, 1.0, v54
	v_max_f32_e32 v55, 1.0, v55
	v_max_f32_e32 v56, 1.0, v56
	v_max_f32_e32 v57, 1.0, v57
	v_max_f32_e32 v50, 1.0, v50
	v_max_f32_e32 v51, 1.0, v51
	v_max_f32_e32 v52, 1.0, v52
	v_max_f32_e32 v53, 1.0, v53
	v_cvt_pk_u8_f32 v156, v54, 0, 0
	v_cvt_pk_u8_f32 v157, v50, 0, 0
	v_cvt_pk_u8_f32 v156, v55, 1, v156
	v_cvt_pk_u8_f32 v157, v51, 1, v157
	v_cvt_pk_u8_f32 v156, v56, 2, v156
	v_cvt_pk_u8_f32 v157, v52, 2, v157
	v_cvt_pk_u8_f32 v156, v57, 3, v156
	v_cvt_pk_u8_f32 v157, v53, 3, v157
	global_store_dwordx2 v153, v[156:157], s[24:25] offset:128
	v_mul_f32_e32 v46, v46, v143
	v_mul_f32_e32 v47, v47, v143
	v_mul_f32_e32 v48, v48, v143
	v_mul_f32_e32 v49, v49, v143
	v_mul_f32_e32 v42, v42, v143
	v_mul_f32_e32 v43, v43, v143
	v_mul_f32_e32 v44, v44, v143
	v_mul_f32_e32 v45, v45, v143
	v_mul_f32_e32 v46, s2, v46
	v_mul_f32_e32 v47, s2, v47
	v_mul_f32_e32 v48, s2, v48
	v_mul_f32_e32 v49, s2, v49
	v_mul_f32_e32 v42, s2, v42
	v_mul_f32_e32 v43, s2, v43
	v_mul_f32_e32 v44, s2, v44
	v_mul_f32_e32 v45, s2, v45
	v_exp_f32_e32 v46, v46
	v_exp_f32_e32 v47, v47
	v_exp_f32_e32 v48, v48
	v_exp_f32_e32 v49, v49
	v_exp_f32_e32 v42, v42
	v_exp_f32_e32 v43, v43
	v_exp_f32_e32 v44, v44
	v_exp_f32_e32 v45, v45
	v_add_f32_e32 v46, 1.0, v46
	v_add_f32_e32 v47, 1.0, v47
	v_add_f32_e32 v48, 1.0, v48
	v_add_f32_e32 v49, 1.0, v49
	v_add_f32_e32 v42, 1.0, v42
	v_add_f32_e32 v43, 1.0, v43
	v_add_f32_e32 v44, 1.0, v44
	v_add_f32_e32 v45, 1.0, v45
	v_rcp_f32_e32 v46, v46
	v_rcp_f32_e32 v47, v47
	v_rcp_f32_e32 v48, v48
	v_rcp_f32_e32 v49, v49
	v_rcp_f32_e32 v42, v42
	v_rcp_f32_e32 v43, v43
	v_rcp_f32_e32 v44, v44
	v_rcp_f32_e32 v45, v45
	v_mul_f32_e32 v46, s3, v46
	v_mul_f32_e32 v47, s3, v47
	v_mul_f32_e32 v48, s3, v48
	v_mul_f32_e32 v49, s3, v49
	v_mul_f32_e32 v42, s3, v42
	v_mul_f32_e32 v43, s3, v43
	v_mul_f32_e32 v44, s3, v44
	v_mul_f32_e32 v45, s3, v45
	v_max_f32_e32 v46, 1.0, v46
	v_max_f32_e32 v47, 1.0, v47
	v_max_f32_e32 v48, 1.0, v48
	v_max_f32_e32 v49, 1.0, v49
	v_max_f32_e32 v42, 1.0, v42
	v_max_f32_e32 v43, 1.0, v43
	v_max_f32_e32 v44, 1.0, v44
	v_max_f32_e32 v45, 1.0, v45
	v_cvt_pk_u8_f32 v154, v46, 0, 0
	v_cvt_pk_u8_f32 v155, v42, 0, 0
	v_cvt_pk_u8_f32 v154, v47, 1, v154
	v_cvt_pk_u8_f32 v155, v43, 1, v155
	v_cvt_pk_u8_f32 v154, v48, 2, v154
	v_cvt_pk_u8_f32 v155, v44, 2, v155
	v_cvt_pk_u8_f32 v154, v49, 3, v154
	v_cvt_pk_u8_f32 v155, v45, 3, v155
	v_add_u32_e32 v153, 0x10000, v153
	global_store_dwordx2 v153, v[154:155], s[24:25]
	v_mul_f32_e32 v38, v38, v143
	v_mul_f32_e32 v39, v39, v143
	v_mul_f32_e32 v40, v40, v143
	v_mul_f32_e32 v41, v41, v143
	v_mul_f32_e32 v34, v34, v143
	v_mul_f32_e32 v35, v35, v143
	v_mul_f32_e32 v36, v36, v143
	v_mul_f32_e32 v37, v37, v143
	v_mul_f32_e32 v38, s2, v38
	v_mul_f32_e32 v39, s2, v39
	v_mul_f32_e32 v40, s2, v40
	v_mul_f32_e32 v41, s2, v41
	v_mul_f32_e32 v34, s2, v34
	v_mul_f32_e32 v35, s2, v35
	v_mul_f32_e32 v36, s2, v36
	v_mul_f32_e32 v37, s2, v37
	v_exp_f32_e32 v38, v38
	v_exp_f32_e32 v39, v39
	v_exp_f32_e32 v40, v40
	v_exp_f32_e32 v41, v41
	v_exp_f32_e32 v34, v34
	v_exp_f32_e32 v35, v35
	v_exp_f32_e32 v36, v36
	v_exp_f32_e32 v37, v37
	v_add_f32_e32 v38, 1.0, v38
	v_add_f32_e32 v39, 1.0, v39
	v_add_f32_e32 v40, 1.0, v40
	v_add_f32_e32 v41, 1.0, v41
	v_add_f32_e32 v34, 1.0, v34
	v_add_f32_e32 v35, 1.0, v35
	v_add_f32_e32 v36, 1.0, v36
	v_add_f32_e32 v37, 1.0, v37
	v_rcp_f32_e32 v38, v38
	v_rcp_f32_e32 v39, v39
	v_rcp_f32_e32 v40, v40
	v_rcp_f32_e32 v41, v41
	v_rcp_f32_e32 v34, v34
; __device__ __forceinline__ float sigmoidf_(float x) { return rcpf(1.0f + __expf(-x)); }
; __device__ __forceinline__ float gelu_tanh(float v) { const float u = 0.7978845608f * (v + 0.044715f * v * v * v); return v * rcpf(1.0f + __expf(-2.0f * u)); }
;     __device__ __forceinline__ void operator()(const f32x4 (&acc)[2][2][4][2], const Unit& u, int wr, int wc, int fr, int fq) const {
;     ...
;             for (int m = 0; m < 4; ++m) { const size_t row = (size_t)(row0 + ai * HALF + m * 16); const float rs = rsv[ai][m];
; #pragma unroll
;                 for (int bj = 0; bj < 2; ++bj) { float o[8];
;                     const int c0 = u.pn * BM + bj * HALF + wc * 32 + 8 * fq;
; #pragma unroll
;                     for (int n = 0; n < 2; ++n)
; #pragma unroll
;                         for (int j = 0; j < 4; ++j) { const float v = acc[ai][bj][m][n][j] * rs; o[n * 4 + j] = mode == 0 ? gelu_tanh(v) : (mode == 1 ? v : sigmoidf_(v)); }
;                     if (mode == 2) { unsigned w0 = 0u, w1 = 0u;
; #pragma unroll
;                         for (int j = 0; j < 4; ++j) { w0 = __builtin_amdgcn_cvt_pk_u8_f32(fmaxf(o[j] * 255.f, 1.f), j, w0); w1 = __builtin_amdgcn_cvt_pk_u8_f32(fmaxf(o[4 + j] * 255.f, 1.f), j, w1); }
;                         u32x2 wv; wv.x = w0; wv.y = w1; *(u32x2*)(gates + row * 4096 + (c0 - 5120)) = wv; }
	v_rcp_f32_e32 v35, v35
	v_rcp_f32_e32 v36, v36
	v_rcp_f32_e32 v37, v37
	v_mul_f32_e32 v38, s3, v38
	v_mul_f32_e32 v39, s3, v39
	v_mul_f32_e32 v40, s3, v40
	v_mul_f32_e32 v41, s3, v41
	v_mul_f32_e32 v34, s3, v34
	v_mul_f32_e32 v35, s3, v35
	v_mul_f32_e32 v36, s3, v36
	v_mul_f32_e32 v37, s3, v37
	v_max_f32_e32 v38, 1.0, v38
	v_max_f32_e32 v39, 1.0, v39
	v_max_f32_e32 v40, 1.0, v40
	v_max_f32_e32 v41, 1.0, v41
	v_max_f32_e32 v34, 1.0, v34
	v_max_f32_e32 v35, 1.0, v35
	v_max_f32_e32 v36, 1.0, v36
	v_max_f32_e32 v37, 1.0, v37
	v_cvt_pk_u8_f32 v156, v38, 0, 0
	v_cvt_pk_u8_f32 v157, v34, 0, 0
	v_cvt_pk_u8_f32 v156, v39, 1, v156
	v_cvt_pk_u8_f32 v157, v35, 1, v157
	v_cvt_pk_u8_f32 v156, v40, 2, v156
	v_cvt_pk_u8_f32 v157, v36, 2, v157
	v_cvt_pk_u8_f32 v156, v41, 3, v156
	v_cvt_pk_u8_f32 v157, v37, 3, v157
	global_store_dwordx2 v153, v[156:157], s[24:25] offset:128
	v_mul_f32_e32 v30, v30, v140
	v_mul_f32_e32 v31, v31, v140
	v_mul_f32_e32 v32, v32, v140
	v_mul_f32_e32 v33, v33, v140
	v_mul_f32_e32 v26, v26, v140
	v_mul_f32_e32 v27, v27, v140
	v_mul_f32_e32 v28, v28, v140
	v_mul_f32_e32 v29, v29, v140
	v_mul_f32_e32 v30, s2, v30
	v_mul_f32_e32 v31, s2, v31
	v_mul_f32_e32 v32, s2, v32
	v_mul_f32_e32 v33, s2, v33
	v_mul_f32_e32 v26, s2, v26
	v_mul_f32_e32 v27, s2, v27
	v_mul_f32_e32 v28, s2, v28
	v_mul_f32_e32 v29, s2, v29
	v_exp_f32_e32 v30, v30
	v_exp_f32_e32 v31, v31
	v_exp_f32_e32 v32, v32
	v_exp_f32_e32 v33, v33
	v_exp_f32_e32 v26, v26
	v_exp_f32_e32 v27, v27
	v_exp_f32_e32 v28, v28
	v_exp_f32_e32 v29, v29
	v_add_f32_e32 v30, 1.0, v30
	v_add_f32_e32 v31, 1.0, v31
	v_add_f32_e32 v32, 1.0, v32
	v_add_f32_e32 v33, 1.0, v33
	v_add_f32_e32 v26, 1.0, v26
	v_add_f32_e32 v27, 1.0, v27
	v_add_f32_e32 v28, 1.0, v28
	v_add_f32_e32 v29, 1.0, v29
	v_rcp_f32_e32 v30, v30
	v_rcp_f32_e32 v31, v31
	v_rcp_f32_e32 v32, v32
	v_rcp_f32_e32 v33, v33
	v_rcp_f32_e32 v26, v26
	v_rcp_f32_e32 v27, v27
	v_rcp_f32_e32 v28, v28
	v_rcp_f32_e32 v29, v29
	v_mul_f32_e32 v30, s3, v30
	v_mul_f32_e32 v31, s3, v31
	v_mul_f32_e32 v32, s3, v32
	v_mul_f32_e32 v33, s3, v33
	v_mul_f32_e32 v26, s3, v26
	v_mul_f32_e32 v27, s3, v27
	v_mul_f32_e32 v28, s3, v28
	v_mul_f32_e32 v29, s3, v29
	v_max_f32_e32 v30, 1.0, v30
	v_max_f32_e32 v31, 1.0, v31
	v_max_f32_e32 v32, 1.0, v32
	v_max_f32_e32 v33, 1.0, v33
	v_max_f32_e32 v26, 1.0, v26
	v_max_f32_e32 v27, 1.0, v27
	v_max_f32_e32 v28, 1.0, v28
	v_max_f32_e32 v29, 1.0, v29
	v_cvt_pk_u8_f32 v154, v30, 0, 0
	v_cvt_pk_u8_f32 v155, v26, 0, 0
	v_cvt_pk_u8_f32 v154, v31, 1, v154
	v_cvt_pk_u8_f32 v155, v27, 1, v155
	v_cvt_pk_u8_f32 v154, v32, 2, v154
	v_cvt_pk_u8_f32 v155, v28, 2, v155
	v_cvt_pk_u8_f32 v154, v33, 3, v154
	v_cvt_pk_u8_f32 v155, v29, 3, v155
	v_add_u32_e32 v153, 0x10000, v153
	global_store_dwordx2 v153, v[154:155], s[24:25]
	v_mul_f32_e32 v22, v22, v140
	v_mul_f32_e32 v23, v23, v140
	v_mul_f32_e32 v24, v24, v140
	v_mul_f32_e32 v25, v25, v140
	v_mul_f32_e32 v18, v18, v140
	v_mul_f32_e32 v19, v19, v140
	v_mul_f32_e32 v20, v20, v140
	v_mul_f32_e32 v21, v21, v140
	v_mul_f32_e32 v22, s2, v22
	v_mul_f32_e32 v23, s2, v23
	v_mul_f32_e32 v24, s2, v24
	v_mul_f32_e32 v25, s2, v25
	v_mul_f32_e32 v18, s2, v18
	v_mul_f32_e32 v19, s2, v19
	v_mul_f32_e32 v20, s2, v20
	v_mul_f32_e32 v21, s2, v21
	v_exp_f32_e32 v22, v22
	v_exp_f32_e32 v23, v23
	v_exp_f32_e32 v24, v24
	v_exp_f32_e32 v25, v25
	v_exp_f32_e32 v18, v18
	v_exp_f32_e32 v19, v19
	v_exp_f32_e32 v20, v20
	v_exp_f32_e32 v21, v21
	v_add_f32_e32 v22, 1.0, v22
	v_add_f32_e32 v23, 1.0, v23
	v_add_f32_e32 v24, 1.0, v24
	v_add_f32_e32 v25, 1.0, v25
	v_add_f32_e32 v18, 1.0, v18
	v_add_f32_e32 v19, 1.0, v19
	v_add_f32_e32 v20, 1.0, v20
	v_add_f32_e32 v21, 1.0, v21
	v_rcp_f32_e32 v22, v22
	v_rcp_f32_e32 v23, v23
	v_rcp_f32_e32 v24, v24
	v_rcp_f32_e32 v25, v25
	v_rcp_f32_e32 v18, v18
	v_rcp_f32_e32 v19, v19
	v_rcp_f32_e32 v20, v20
	v_rcp_f32_e32 v21, v21
	v_mul_f32_e32 v22, s3, v22
	v_mul_f32_e32 v23, s3, v23
	v_mul_f32_e32 v24, s3, v24
	v_mul_f32_e32 v25, s3, v25
	v_mul_f32_e32 v18, s3, v18
	v_mul_f32_e32 v19, s3, v19
	v_mul_f32_e32 v20, s3, v20
	v_mul_f32_e32 v21, s3, v21
	v_max_f32_e32 v22, 1.0, v22
	v_max_f32_e32 v23, 1.0, v23
	v_max_f32_e32 v24, 1.0, v24
	v_max_f32_e32 v25, 1.0, v25
	v_max_f32_e32 v18, 1.0, v18
	v_max_f32_e32 v19, 1.0, v19
; __device__ __forceinline__ float sigmoidf_(float x) { return rcpf(1.0f + __expf(-x)); }
; __device__ __forceinline__ float gelu_tanh(float v) { const float u = 0.7978845608f * (v + 0.044715f * v * v * v); return v * rcpf(1.0f + __expf(-2.0f * u)); }
;     __device__ __forceinline__ void operator()(const f32x4 (&acc)[2][2][4][2], const Unit& u, int wr, int wc, int fr, int fq) const {
;     ...
;             for (int m = 0; m < 4; ++m) { const size_t row = (size_t)(row0 + ai * HALF + m * 16); const float rs = rsv[ai][m];
; #pragma unroll
;                 for (int bj = 0; bj < 2; ++bj) { float o[8];
;                     const int c0 = u.pn * BM + bj * HALF + wc * 32 + 8 * fq;
; #pragma unroll
;                     for (int n = 0; n < 2; ++n)
; #pragma unroll
;                         for (int j = 0; j < 4; ++j) { const float v = acc[ai][bj][m][n][j] * rs; o[n * 4 + j] = mode == 0 ? gelu_tanh(v) : (mode == 1 ? v : sigmoidf_(v)); }
;                     if (mode == 2) { unsigned w0 = 0u, w1 = 0u;
; #pragma unroll
;                         for (int j = 0; j < 4; ++j) { w0 = __builtin_amdgcn_cvt_pk_u8_f32(fmaxf(o[j] * 255.f, 1.f), j, w0); w1 = __builtin_amdgcn_cvt_pk_u8_f32(fmaxf(o[4 + j] * 255.f, 1.f), j, w1); }
;                         u32x2 wv; wv.x = w0; wv.y = w1; *(u32x2*)(gates + row * 4096 + (c0 - 5120)) = wv; }
	v_max_f32_e32 v20, 1.0, v20
	v_max_f32_e32 v21, 1.0, v21
	v_cvt_pk_u8_f32 v156, v22, 0, 0
	v_cvt_pk_u8_f32 v157, v18, 0, 0
	v_cvt_pk_u8_f32 v156, v23, 1, v156
	v_cvt_pk_u8_f32 v157, v19, 1, v157
	v_cvt_pk_u8_f32 v156, v24, 2, v156
	v_cvt_pk_u8_f32 v157, v20, 2, v157
	v_cvt_pk_u8_f32 v156, v25, 3, v156
	v_cvt_pk_u8_f32 v157, v21, 3, v157
	global_store_dwordx2 v153, v[156:157], s[24:25] offset:128
	v_mul_f32_e32 v14, v14, v141
	v_mul_f32_e32 v15, v15, v141
	v_mul_f32_e32 v16, v16, v141
	v_mul_f32_e32 v17, v17, v141
	v_mul_f32_e32 v10, v10, v141
	v_mul_f32_e32 v11, v11, v141
	v_mul_f32_e32 v12, v12, v141
	v_mul_f32_e32 v13, v13, v141
	v_mul_f32_e32 v14, s2, v14
	v_mul_f32_e32 v15, s2, v15
	v_mul_f32_e32 v16, s2, v16
	v_mul_f32_e32 v17, s2, v17
	v_mul_f32_e32 v10, s2, v10
	v_mul_f32_e32 v11, s2, v11
	v_mul_f32_e32 v12, s2, v12
	v_mul_f32_e32 v13, s2, v13
	v_exp_f32_e32 v14, v14
	v_exp_f32_e32 v15, v15
	v_exp_f32_e32 v16, v16
	v_exp_f32_e32 v17, v17
	v_exp_f32_e32 v10, v10
	v_exp_f32_e32 v11, v11
	v_exp_f32_e32 v12, v12
	v_exp_f32_e32 v13, v13
	v_add_f32_e32 v14, 1.0, v14
	v_add_f32_e32 v15, 1.0, v15
	v_add_f32_e32 v16, 1.0, v16
	v_add_f32_e32 v17, 1.0, v17
	v_add_f32_e32 v10, 1.0, v10
	v_add_f32_e32 v11, 1.0, v11
	v_add_f32_e32 v12, 1.0, v12
	v_add_f32_e32 v13, 1.0, v13
	v_rcp_f32_e32 v14, v14
	v_rcp_f32_e32 v15, v15
	v_rcp_f32_e32 v16, v16
	v_rcp_f32_e32 v17, v17
	v_rcp_f32_e32 v10, v10
	v_rcp_f32_e32 v11, v11
	v_rcp_f32_e32 v12, v12
	v_rcp_f32_e32 v13, v13
	v_mul_f32_e32 v14, s3, v14
	v_mul_f32_e32 v15, s3, v15
	v_mul_f32_e32 v16, s3, v16
	v_mul_f32_e32 v17, s3, v17
	v_mul_f32_e32 v10, s3, v10
	v_mul_f32_e32 v11, s3, v11
	v_mul_f32_e32 v12, s3, v12
	v_mul_f32_e32 v13, s3, v13
	v_max_f32_e32 v14, 1.0, v14
	v_max_f32_e32 v15, 1.0, v15
	v_max_f32_e32 v16, 1.0, v16
	v_max_f32_e32 v17, 1.0, v17
	v_max_f32_e32 v10, 1.0, v10
	v_max_f32_e32 v11, 1.0, v11
	v_max_f32_e32 v12, 1.0, v12
	v_max_f32_e32 v13, 1.0, v13
	v_cvt_pk_u8_f32 v154, v14, 0, 0
	v_cvt_pk_u8_f32 v155, v10, 0, 0
	v_cvt_pk_u8_f32 v154, v15, 1, v154
	v_cvt_pk_u8_f32 v155, v11, 1, v155
	v_cvt_pk_u8_f32 v154, v16, 2, v154
	v_cvt_pk_u8_f32 v155, v12, 2, v155
	v_cvt_pk_u8_f32 v154, v17, 3, v154
	v_cvt_pk_u8_f32 v155, v13, 3, v155
	v_add_u32_e32 v153, 0x10000, v153
	global_store_dwordx2 v153, v[154:155], s[24:25]
	v_mul_f32_e32 v6, v6, v141
	v_mul_f32_e32 v7, v7, v141
	v_mul_f32_e32 v8, v8, v141
	v_mul_f32_e32 v9, v9, v141
	v_mul_f32_e32 v2, v2, v141
	v_mul_f32_e32 v3, v3, v141
	v_mul_f32_e32 v4, v4, v141
	v_mul_f32_e32 v5, v5, v141
	v_mul_f32_e32 v6, s2, v6
	v_mul_f32_e32 v7, s2, v7
	v_mul_f32_e32 v8, s2, v8
	v_mul_f32_e32 v9, s2, v9
	v_mul_f32_e32 v2, s2, v2
	v_mul_f32_e32 v3, s2, v3
	v_mul_f32_e32 v4, s2, v4
	v_mul_f32_e32 v5, s2, v5
	v_exp_f32_e32 v6, v6
	v_exp_f32_e32 v7, v7
	v_exp_f32_e32 v8, v8
	v_exp_f32_e32 v9, v9
	v_exp_f32_e32 v2, v2
	v_exp_f32_e32 v3, v3
	v_exp_f32_e32 v4, v4
	v_exp_f32_e32 v5, v5
	v_add_f32_e32 v6, 1.0, v6
	v_add_f32_e32 v7, 1.0, v7
	v_add_f32_e32 v8, 1.0, v8
	v_add_f32_e32 v9, 1.0, v9
	v_add_f32_e32 v2, 1.0, v2
	v_add_f32_e32 v3, 1.0, v3
	v_add_f32_e32 v4, 1.0, v4
	v_add_f32_e32 v5, 1.0, v5
	v_rcp_f32_e32 v6, v6
	v_rcp_f32_e32 v7, v7
	v_rcp_f32_e32 v8, v8
	v_rcp_f32_e32 v9, v9
	v_rcp_f32_e32 v2, v2
	v_rcp_f32_e32 v3, v3
	v_rcp_f32_e32 v4, v4
	v_rcp_f32_e32 v5, v5
	v_mul_f32_e32 v6, s3, v6
	v_mul_f32_e32 v7, s3, v7
	v_mul_f32_e32 v8, s3, v8
	v_mul_f32_e32 v9, s3, v9
	v_mul_f32_e32 v2, s3, v2
	v_mul_f32_e32 v3, s3, v3
	v_mul_f32_e32 v4, s3, v4
	v_mul_f32_e32 v5, s3, v5
	v_max_f32_e32 v6, 1.0, v6
	v_max_f32_e32 v7, 1.0, v7
	v_max_f32_e32 v8, 1.0, v8
	v_max_f32_e32 v9, 1.0, v9
	v_max_f32_e32 v2, 1.0, v2
	v_max_f32_e32 v3, 1.0, v3
	v_max_f32_e32 v4, 1.0, v4
	v_max_f32_e32 v5, 1.0, v5
	v_cvt_pk_u8_f32 v156, v6, 0, 0
	v_cvt_pk_u8_f32 v157, v2, 0, 0
	v_cvt_pk_u8_f32 v156, v7, 1, v156
	v_cvt_pk_u8_f32 v157, v3, 1, v157
	v_cvt_pk_u8_f32 v156, v8, 2, v156
	v_cvt_pk_u8_f32 v157, v4, 2, v157
	v_cvt_pk_u8_f32 v156, v9, 3, v156
	v_cvt_pk_u8_f32 v157, v5, 3, v157
	global_store_dwordx2 v153, v[156:157], s[24:25] offset:128
.Lmy_ip_done:
	s_andn2_b64 vcc, exec, s[36:37]
	s_mov_b64 s[2:3], -1
	s_cbranch_vccnz .LBB0_431
.LBB0_1303:
	s_andn2_b64 vcc, exec, s[0:1]
	s_cbranch_vccnz .LBB0_430
	s_barrier
	s_branch .LBB0_430

; __global__ void __launch_bounds__(NT, 2) mega(Params p) {
	.amdhsa_kernel _Z4mega6Params
		.amdhsa_group_segment_fixed_size 0
		.amdhsa_private_segment_fixed_size 0
		.amdhsa_kernarg_size 520
		.amdhsa_user_sgpr_count 2
		.amdhsa_user_sgpr_dispatch_ptr 0
		.amdhsa_user_sgpr_queue_ptr 0
		.amdhsa_user_sgpr_kernarg_segment_ptr 1
		.amdhsa_user_sgpr_dispatch_id 0
		.amdhsa_user_sgpr_kernarg_preload_length 0
		.amdhsa_user_sgpr_kernarg_preload_offset 0
		.amdhsa_user_sgpr_private_segment_size 0
		.amdhsa_uses_dynamic_stack 0
		.amdhsa_enable_private_segment 0
		.amdhsa_system_sgpr_workgroup_id_x 1
		.amdhsa_system_sgpr_workgroup_id_y 0
		.amdhsa_system_sgpr_workgroup_id_z 0
		.amdhsa_system_sgpr_workgroup_info 0
		.amdhsa_system_vgpr_workitem_id 2
		.amdhsa_next_free_vgpr 256
		.amdhsa_next_free_sgpr 102
		.amdhsa_accum_offset 256
		.amdhsa_reserve_vcc 1
		.amdhsa_float_round_mode_32 0
		.amdhsa_float_round_mode_16_64 0
		.amdhsa_float_denorm_mode_32 3
		.amdhsa_float_denorm_mode_16_64 3
		.amdhsa_dx10_clamp 1
		.amdhsa_ieee_mode 1
		.amdhsa_fp16_overflow 0
		.amdhsa_tg_split 0
		.amdhsa_exception_fp_ieee_invalid_op 0
		.amdhsa_exception_fp_denorm_src 0
		.amdhsa_exception_fp_ieee_div_zero 0
		.amdhsa_exception_fp_ieee_overflow 0
		.amdhsa_exception_fp_ieee_underflow 0
		.amdhsa_exception_fp_ieee_inexact 0
		.amdhsa_exception_int_div_zero 0
	.end_amdhsa_kernel

; __global__ void __launch_bounds__(NT, 2) mega(Params p) {
amdhsa.kernels:
  - .agpr_count:     0
    .args:
      - .offset:         0
        .size:           264
        .value_kind:     by_value
      - .offset:         264
        .size:           4
        .value_kind:     hidden_block_count_x
      - .offset:         268
        .size:           4
        .value_kind:     hidden_block_count_y
      - .offset:         272
        .size:           4
        .value_kind:     hidden_block_count_z
      - .offset:         276
        .size:           2
        .value_kind:     hidden_group_size_x
      - .offset:         278
        .size:           2
        .value_kind:     hidden_group_size_y
      - .offset:         280
        .size:           2
        .value_kind:     hidden_group_size_z
      - .offset:         282
        .size:           2
        .value_kind:     hidden_remainder_x
      - .offset:         284
        .size:           2
        .value_kind:     hidden_remainder_y
      - .offset:         286
        .size:           2
        .value_kind:     hidden_remainder_z
      - .offset:         304
        .size:           8
        .value_kind:     hidden_global_offset_x
      - .offset:         312
        .size:           8
        .value_kind:     hidden_global_offset_y
      - .offset:         320
        .size:           8
        .value_kind:     hidden_global_offset_z
      - .offset:         328
        .size:           2
        .value_kind:     hidden_grid_dims
      - .offset:         352
        .size:           8
        .value_kind:     hidden_multigrid_sync_arg
      - .offset:         384
        .size:           4
        .value_kind:     hidden_dynamic_lds_size
    .group_segment_fixed_size: 0
    .kernarg_segment_align: 8
    .kernarg_segment_size: 520
    .language:       OpenCL C
    .language_version:
      - 2
      - 0
    .max_flat_workgroup_size: 512
    .name:           _Z4mega6Params
    .private_segment_fixed_size: 0
    .sgpr_count:     108
    .sgpr_spill_count: 319
    .symbol:         _Z4mega6Params.kd
    .uniform_work_group_size: 1
    .uses_dynamic_stack: false
    .vgpr_count:     256
    .vgpr_spill_count: 0
    .wavefront_size: 64
